# P5 sample instance: intra-chunk V-fragment loads issued right after the q.k^T chain
# baseline (speedup 1.0000x reference)
; #define MFMA32(a, b, c) __builtin_amdgcn_mfma_f32_32x32x16_bf16((a), (b), (c), 0, 0, 0)
; __device__ __forceinline__ s16x8 pack8(const float (&x)[8]) { u32x4 p; p.x = pk2(x[0], x[1]); p.y = pk2(x[2], x[3]); p.z = pk2(x[4], x[5]); p.w = pk2(x[6], x[7]); return __builtin_bit_cast(s16x8, p); }
; template <bool SAMPLE>
; __device__ __forceinline__ void mout_task(Ctx& C, int l, int unit, int h, int tb, const LAS float* cwl, const LAS float* gainl, LAS float* gsbuf, LAS s16x8* qfl, const bool st) {
;     ...
;     if (SAMPLE) {
;         const float* cp = C.in[5] + ((size_t)l * NSLOT_S + unit * 4 + h) * 16384 + r;
; #pragma unroll 1
;         for (int ks = 0; ks < 8; ++ks) { const s16x8 qv = qfl[ks * 64 + lane];
; #pragma unroll
;             for (int vb = 0; vb < 4; ++vb) { float x[8];
; #pragma unroll
;                 for (int e = 0; e < 8; ++e) x[e] = cp[(size_t)(16 * ks + 8 * hi + e) * 128 + 32 * vb];
;                 acc[vb] = MFMA32(pack8(x), qv, acc[vb]); } }
.LBB0_920:
	global_load_dword v132, v[36:37], off offset:-2048
	global_load_dword v133, v[36:37], off offset:-1536
	global_load_dword v134, v[36:37], off offset:-1024
	global_load_dword v135, v[36:37], off offset:-512
	global_load_dword v136, v[36:37], off
	global_load_dword v137, v[36:37], off offset:512
	global_load_dword v138, v[36:37], off offset:1024
	global_load_dword v139, v[36:37], off offset:1536
	global_load_dword v140, v[36:37], off offset:-1920
	global_load_dword v141, v[36:37], off offset:-1408
	global_load_dword v142, v[36:37], off offset:-896
	global_load_dword v143, v[36:37], off offset:-384
	global_load_dword v144, v[36:37], off offset:128
	global_load_dword v145, v[36:37], off offset:640
	global_load_dword v146, v[36:37], off offset:1152
	global_load_dword v147, v[36:37], off offset:1664
	global_load_dword v148, v[36:37], off offset:-1792
	global_load_dword v149, v[36:37], off offset:-1280
	global_load_dword v150, v[36:37], off offset:-768
	global_load_dword v151, v[36:37], off offset:-256
	global_load_dword v152, v[36:37], off offset:256
	global_load_dword v153, v[36:37], off offset:768
	global_load_dword v154, v[36:37], off offset:1280
	global_load_dword v155, v[36:37], off offset:1792
	global_load_dword v156, v[36:37], off offset:-1664
	global_load_dword v157, v[36:37], off offset:-1152
	global_load_dword v158, v[36:37], off offset:-640
	global_load_dword v159, v[36:37], off offset:-128
	global_load_dword v160, v[36:37], off offset:384
	global_load_dword v161, v[36:37], off offset:896
	global_load_dword v162, v[36:37], off offset:1408
	global_load_dword v163, v[36:37], off offset:1920
	v_lshl_add_u64 v[36:37], v[36:37], 0, s[28:29]
	global_load_dword v164, v[36:37], off offset:-2048
	global_load_dword v165, v[36:37], off offset:-1536
	global_load_dword v166, v[36:37], off offset:-1024
	global_load_dword v167, v[36:37], off offset:-512
	global_load_dword v168, v[36:37], off
	global_load_dword v169, v[36:37], off offset:512
	global_load_dword v170, v[36:37], off offset:1024
	global_load_dword v171, v[36:37], off offset:1536
	global_load_dword v172, v[36:37], off offset:-1920
	global_load_dword v173, v[36:37], off offset:-1408
	global_load_dword v174, v[36:37], off offset:-896
	global_load_dword v175, v[36:37], off offset:-384
	global_load_dword v176, v[36:37], off offset:128
	global_load_dword v177, v[36:37], off offset:640
	global_load_dword v178, v[36:37], off offset:1152
	global_load_dword v179, v[36:37], off offset:1664
	global_load_dword v180, v[36:37], off offset:-1792
	global_load_dword v181, v[36:37], off offset:-1280
	global_load_dword v182, v[36:37], off offset:-768
	global_load_dword v183, v[36:37], off offset:-256
	global_load_dword v184, v[36:37], off offset:256
	global_load_dword v47, v[36:37], off offset:768
	global_load_dword v48, v[36:37], off offset:1280
	global_load_dword v49, v[36:37], off offset:1792
	global_load_dword v50, v[36:37], off offset:-1664
	global_load_dword v51, v[36:37], off offset:-1152
	global_load_dword v52, v[36:37], off offset:-640
	global_load_dword v53, v[36:37], off offset:-128
	global_load_dword v54, v[36:37], off offset:384
	global_load_dword v55, v[36:37], off offset:896
	global_load_dword v56, v[36:37], off offset:1408
	global_load_dword v57, v[36:37], off offset:1920
	v_lshl_add_u64 v[36:37], v[36:37], 0, s[28:29]
	ds_read_b128 v[32:35], v131
	ds_read_b128 v[104:107], v131 offset:1024
	s_waitcnt vmcnt(56) lgkmcnt(1)
	v_cvt_pk_bf16_f32 v40, v132, v133
	v_cvt_pk_bf16_f32 v41, v134, v135
	v_cvt_pk_bf16_f32 v42, v136, v137
	v_cvt_pk_bf16_f32 v43, v138, v139
	global_load_dword v132, v[36:37], off offset:-2048
	global_load_dword v133, v[36:37], off offset:-1536
	global_load_dword v134, v[36:37], off offset:-1024
	global_load_dword v135, v[36:37], off offset:-512
	global_load_dword v136, v[36:37], off
	global_load_dword v137, v[36:37], off offset:512
	global_load_dword v138, v[36:37], off offset:1024
	global_load_dword v139, v[36:37], off offset:1536
	v_mfma_f32_32x32x16_bf16 v[0:15], v[40:43], v[32:35], v[0:15]
	s_waitcnt vmcnt(56)
	v_cvt_pk_bf16_f32 v60, v140, v141
	v_cvt_pk_bf16_f32 v61, v142, v143
	v_cvt_pk_bf16_f32 v62, v144, v145
	v_cvt_pk_bf16_f32 v63, v146, v147
	global_load_dword v140, v[36:37], off offset:-1920
	global_load_dword v141, v[36:37], off offset:-1408
	global_load_dword v142, v[36:37], off offset:-896
	global_load_dword v143, v[36:37], off offset:-384
	global_load_dword v144, v[36:37], off offset:128
	global_load_dword v145, v[36:37], off offset:640
	global_load_dword v146, v[36:37], off offset:1152
	global_load_dword v147, v[36:37], off offset:1664
	v_mfma_f32_32x32x16_bf16 v[16:31], v[60:63], v[32:35], v[16:31]
	s_waitcnt vmcnt(56)
	v_cvt_pk_bf16_f32 v40, v148, v149
	v_cvt_pk_bf16_f32 v41, v150, v151
	v_cvt_pk_bf16_f32 v42, v152, v153
	v_cvt_pk_bf16_f32 v43, v154, v155
	global_load_dword v148, v[36:37], off offset:-1792
	global_load_dword v149, v[36:37], off offset:-1280
	global_load_dword v150, v[36:37], off offset:-768
	global_load_dword v151, v[36:37], off offset:-256
	global_load_dword v152, v[36:37], off offset:256
	global_load_dword v153, v[36:37], off offset:768
	global_load_dword v154, v[36:37], off offset:1280
	global_load_dword v155, v[36:37], off offset:1792
	v_mfma_f32_32x32x16_bf16 v[64:79], v[40:43], v[32:35], v[64:79]
	s_waitcnt vmcnt(56)
; #define MFMA32(a, b, c) __builtin_amdgcn_mfma_f32_32x32x16_bf16((a), (b), (c), 0, 0, 0)
; __device__ __forceinline__ s16x8 pack8(const float (&x)[8]) { u32x4 p; p.x = pk2(x[0], x[1]); p.y = pk2(x[2], x[3]); p.z = pk2(x[4], x[5]); p.w = pk2(x[6], x[7]); return __builtin_bit_cast(s16x8, p); }
; template <bool SAMPLE>
; __device__ __forceinline__ void mout_task(Ctx& C, int l, int unit, int h, int tb, const LAS float* cwl, const LAS float* gainl, LAS float* gsbuf, LAS s16x8* qfl, const bool st) {
;     ...
;         for (int ks = 0; ks < 8; ++ks) { const s16x8 qv = qfl[ks * 64 + lane];
; #pragma unroll
;             for (int vb = 0; vb < 4; ++vb) { float x[8];
; #pragma unroll
;                 for (int e = 0; e < 8; ++e) x[e] = cp[(size_t)(16 * ks + 8 * hi + e) * 128 + 32 * vb];
;                 acc[vb] = MFMA32(pack8(x), qv, acc[vb]); } }
	v_cvt_pk_bf16_f32 v60, v156, v157
	v_cvt_pk_bf16_f32 v61, v158, v159
	v_cvt_pk_bf16_f32 v62, v160, v161
	v_cvt_pk_bf16_f32 v63, v162, v163
	global_load_dword v156, v[36:37], off offset:-1664
	global_load_dword v157, v[36:37], off offset:-1152
	global_load_dword v158, v[36:37], off offset:-640
	global_load_dword v159, v[36:37], off offset:-128
	global_load_dword v160, v[36:37], off offset:384
	global_load_dword v161, v[36:37], off offset:896
	global_load_dword v162, v[36:37], off offset:1408
	global_load_dword v163, v[36:37], off offset:1920
	v_mfma_f32_32x32x16_bf16 v[80:95], v[60:63], v[32:35], v[80:95]
	v_lshl_add_u64 v[36:37], v[36:37], 0, s[28:29]
	ds_read_b128 v[32:35], v131 offset:2048
	s_waitcnt vmcnt(56) lgkmcnt(1)
	v_cvt_pk_bf16_f32 v40, v164, v165
	v_cvt_pk_bf16_f32 v41, v166, v167
	v_cvt_pk_bf16_f32 v42, v168, v169
	v_cvt_pk_bf16_f32 v43, v170, v171
	global_load_dword v164, v[36:37], off offset:-2048
	global_load_dword v165, v[36:37], off offset:-1536
	global_load_dword v166, v[36:37], off offset:-1024
	global_load_dword v167, v[36:37], off offset:-512
	global_load_dword v168, v[36:37], off
	global_load_dword v169, v[36:37], off offset:512
	global_load_dword v170, v[36:37], off offset:1024
	global_load_dword v171, v[36:37], off offset:1536
	v_mfma_f32_32x32x16_bf16 v[0:15], v[40:43], v[104:107], v[0:15]
	s_waitcnt vmcnt(56)
	v_cvt_pk_bf16_f32 v60, v172, v173
	v_cvt_pk_bf16_f32 v61, v174, v175
	v_cvt_pk_bf16_f32 v62, v176, v177
	v_cvt_pk_bf16_f32 v63, v178, v179
	global_load_dword v172, v[36:37], off offset:-1920
	global_load_dword v173, v[36:37], off offset:-1408
	global_load_dword v174, v[36:37], off offset:-896
	global_load_dword v175, v[36:37], off offset:-384
	global_load_dword v176, v[36:37], off offset:128
	global_load_dword v177, v[36:37], off offset:640
	global_load_dword v178, v[36:37], off offset:1152
	global_load_dword v179, v[36:37], off offset:1664
	v_mfma_f32_32x32x16_bf16 v[16:31], v[60:63], v[104:107], v[16:31]
	s_waitcnt vmcnt(56)
	v_cvt_pk_bf16_f32 v40, v180, v181
	v_cvt_pk_bf16_f32 v41, v182, v183
	v_cvt_pk_bf16_f32 v42, v184, v47
	v_cvt_pk_bf16_f32 v43, v48, v49
	global_load_dword v180, v[36:37], off offset:-1792
	global_load_dword v181, v[36:37], off offset:-1280
	global_load_dword v182, v[36:37], off offset:-768
	global_load_dword v183, v[36:37], off offset:-256
	global_load_dword v184, v[36:37], off offset:256
	global_load_dword v47, v[36:37], off offset:768
	global_load_dword v48, v[36:37], off offset:1280
	global_load_dword v49, v[36:37], off offset:1792
	v_mfma_f32_32x32x16_bf16 v[64:79], v[40:43], v[104:107], v[64:79]
	s_waitcnt vmcnt(56)
	v_cvt_pk_bf16_f32 v60, v50, v51
	v_cvt_pk_bf16_f32 v61, v52, v53
	v_cvt_pk_bf16_f32 v62, v54, v55
	v_cvt_pk_bf16_f32 v63, v56, v57
	global_load_dword v50, v[36:37], off offset:-1664
	global_load_dword v51, v[36:37], off offset:-1152
	global_load_dword v52, v[36:37], off offset:-640
	global_load_dword v53, v[36:37], off offset:-128
	global_load_dword v54, v[36:37], off offset:384
	global_load_dword v55, v[36:37], off offset:896
	global_load_dword v56, v[36:37], off offset:1408
	global_load_dword v57, v[36:37], off offset:1920
	v_mfma_f32_32x32x16_bf16 v[80:95], v[60:63], v[104:107], v[80:95]
	v_lshl_add_u64 v[36:37], v[36:37], 0, s[28:29]
	ds_read_b128 v[104:107], v131 offset:3072
	s_waitcnt vmcnt(56) lgkmcnt(1)
	v_cvt_pk_bf16_f32 v40, v132, v133
	v_cvt_pk_bf16_f32 v41, v134, v135
	v_cvt_pk_bf16_f32 v42, v136, v137
	v_cvt_pk_bf16_f32 v43, v138, v139
	global_load_dword v132, v[36:37], off offset:-2048
	global_load_dword v133, v[36:37], off offset:-1536
	global_load_dword v134, v[36:37], off offset:-1024
	global_load_dword v135, v[36:37], off offset:-512
	global_load_dword v136, v[36:37], off
	global_load_dword v137, v[36:37], off offset:512
	global_load_dword v138, v[36:37], off offset:1024
	global_load_dword v139, v[36:37], off offset:1536
	v_mfma_f32_32x32x16_bf16 v[0:15], v[40:43], v[32:35], v[0:15]
	s_waitcnt vmcnt(56)
	v_cvt_pk_bf16_f32 v60, v140, v141
	v_cvt_pk_bf16_f32 v61, v142, v143
	v_cvt_pk_bf16_f32 v62, v144, v145
	v_cvt_pk_bf16_f32 v63, v146, v147
	global_load_dword v140, v[36:37], off offset:-1920
	global_load_dword v141, v[36:37], off offset:-1408
	global_load_dword v142, v[36:37], off offset:-896
	global_load_dword v143, v[36:37], off offset:-384
	global_load_dword v144, v[36:37], off offset:128
	global_load_dword v145, v[36:37], off offset:640
	global_load_dword v146, v[36:37], off offset:1152
	global_load_dword v147, v[36:37], off offset:1664
	v_mfma_f32_32x32x16_bf16 v[16:31], v[60:63], v[32:35], v[16:31]
	s_waitcnt vmcnt(56)
	v_cvt_pk_bf16_f32 v40, v148, v149
	v_cvt_pk_bf16_f32 v41, v150, v151
	v_cvt_pk_bf16_f32 v42, v152, v153
	v_cvt_pk_bf16_f32 v43, v154, v155
	global_load_dword v148, v[36:37], off offset:-1792
	global_load_dword v149, v[36:37], off offset:-1280
	global_load_dword v150, v[36:37], off offset:-768
	global_load_dword v151, v[36:37], off offset:-256
	global_load_dword v152, v[36:37], off offset:256
	global_load_dword v153, v[36:37], off offset:768
	global_load_dword v154, v[36:37], off offset:1280
	global_load_dword v155, v[36:37], off offset:1792
	v_mfma_f32_32x32x16_bf16 v[64:79], v[40:43], v[32:35], v[64:79]
	s_waitcnt vmcnt(56)
	v_cvt_pk_bf16_f32 v60, v156, v157
	v_cvt_pk_bf16_f32 v61, v158, v159
	v_cvt_pk_bf16_f32 v62, v160, v161
	v_cvt_pk_bf16_f32 v63, v162, v163
	global_load_dword v156, v[36:37], off offset:-1664
	global_load_dword v157, v[36:37], off offset:-1152
	global_load_dword v158, v[36:37], off offset:-640
	global_load_dword v159, v[36:37], off offset:-128
	global_load_dword v160, v[36:37], off offset:384
	global_load_dword v161, v[36:37], off offset:896
	global_load_dword v162, v[36:37], off offset:1408
	global_load_dword v163, v[36:37], off offset:1920
	v_mfma_f32_32x32x16_bf16 v[80:95], v[60:63], v[32:35], v[80:95]
	v_lshl_add_u64 v[36:37], v[36:37], 0, s[28:29]
	ds_read_b128 v[32:35], v131 offset:4096
	s_waitcnt vmcnt(56) lgkmcnt(1)
; #define MFMA32(a, b, c) __builtin_amdgcn_mfma_f32_32x32x16_bf16((a), (b), (c), 0, 0, 0)
; __device__ __forceinline__ s16x8 pack8(const float (&x)[8]) { u32x4 p; p.x = pk2(x[0], x[1]); p.y = pk2(x[2], x[3]); p.z = pk2(x[4], x[5]); p.w = pk2(x[6], x[7]); return __builtin_bit_cast(s16x8, p); }
; template <bool SAMPLE>
; __device__ __forceinline__ void mout_task(Ctx& C, int l, int unit, int h, int tb, const LAS float* cwl, const LAS float* gainl, LAS float* gsbuf, LAS s16x8* qfl, const bool st) {
;     ...
;         for (int ks = 0; ks < 8; ++ks) { const s16x8 qv = qfl[ks * 64 + lane];
; #pragma unroll
;             for (int vb = 0; vb < 4; ++vb) { float x[8];
; #pragma unroll
;                 for (int e = 0; e < 8; ++e) x[e] = cp[(size_t)(16 * ks + 8 * hi + e) * 128 + 32 * vb];
;                 acc[vb] = MFMA32(pack8(x), qv, acc[vb]); } }
	v_cvt_pk_bf16_f32 v40, v164, v165
	v_cvt_pk_bf16_f32 v41, v166, v167
	v_cvt_pk_bf16_f32 v42, v168, v169
	v_cvt_pk_bf16_f32 v43, v170, v171
	global_load_dword v164, v[36:37], off offset:-2048
	global_load_dword v165, v[36:37], off offset:-1536
	global_load_dword v166, v[36:37], off offset:-1024
	global_load_dword v167, v[36:37], off offset:-512
	global_load_dword v168, v[36:37], off
	global_load_dword v169, v[36:37], off offset:512
	global_load_dword v170, v[36:37], off offset:1024
	global_load_dword v171, v[36:37], off offset:1536
	v_mfma_f32_32x32x16_bf16 v[0:15], v[40:43], v[104:107], v[0:15]
	s_waitcnt vmcnt(56)
	v_cvt_pk_bf16_f32 v60, v172, v173
	v_cvt_pk_bf16_f32 v61, v174, v175
	v_cvt_pk_bf16_f32 v62, v176, v177
	v_cvt_pk_bf16_f32 v63, v178, v179
	global_load_dword v172, v[36:37], off offset:-1920
	global_load_dword v173, v[36:37], off offset:-1408
	global_load_dword v174, v[36:37], off offset:-896
	global_load_dword v175, v[36:37], off offset:-384
	global_load_dword v176, v[36:37], off offset:128
	global_load_dword v177, v[36:37], off offset:640
	global_load_dword v178, v[36:37], off offset:1152
	global_load_dword v179, v[36:37], off offset:1664
	v_mfma_f32_32x32x16_bf16 v[16:31], v[60:63], v[104:107], v[16:31]
	s_waitcnt vmcnt(56)
	v_cvt_pk_bf16_f32 v40, v180, v181
	v_cvt_pk_bf16_f32 v41, v182, v183
	v_cvt_pk_bf16_f32 v42, v184, v47
	v_cvt_pk_bf16_f32 v43, v48, v49
	global_load_dword v180, v[36:37], off offset:-1792
	global_load_dword v181, v[36:37], off offset:-1280
	global_load_dword v182, v[36:37], off offset:-768
	global_load_dword v183, v[36:37], off offset:-256
	global_load_dword v184, v[36:37], off offset:256
	global_load_dword v47, v[36:37], off offset:768
	global_load_dword v48, v[36:37], off offset:1280
	global_load_dword v49, v[36:37], off offset:1792
	v_mfma_f32_32x32x16_bf16 v[64:79], v[40:43], v[104:107], v[64:79]
	s_waitcnt vmcnt(56)
	v_cvt_pk_bf16_f32 v60, v50, v51
	v_cvt_pk_bf16_f32 v61, v52, v53
	v_cvt_pk_bf16_f32 v62, v54, v55
	v_cvt_pk_bf16_f32 v63, v56, v57
	global_load_dword v50, v[36:37], off offset:-1664
	global_load_dword v51, v[36:37], off offset:-1152
	global_load_dword v52, v[36:37], off offset:-640
	global_load_dword v53, v[36:37], off offset:-128
	global_load_dword v54, v[36:37], off offset:384
	global_load_dword v55, v[36:37], off offset:896
	global_load_dword v56, v[36:37], off offset:1408
	global_load_dword v57, v[36:37], off offset:1920
	v_mfma_f32_32x32x16_bf16 v[80:95], v[60:63], v[104:107], v[80:95]
	v_lshl_add_u64 v[36:37], v[36:37], 0, s[28:29]
	ds_read_b128 v[104:107], v131 offset:5120
	s_waitcnt vmcnt(56) lgkmcnt(1)
	v_cvt_pk_bf16_f32 v40, v132, v133
	v_cvt_pk_bf16_f32 v41, v134, v135
	v_cvt_pk_bf16_f32 v42, v136, v137
	v_cvt_pk_bf16_f32 v43, v138, v139
	global_load_dword v132, v[36:37], off offset:-2048
	global_load_dword v133, v[36:37], off offset:-1536
	global_load_dword v134, v[36:37], off offset:-1024
	global_load_dword v135, v[36:37], off offset:-512
	global_load_dword v136, v[36:37], off
	global_load_dword v137, v[36:37], off offset:512
	global_load_dword v138, v[36:37], off offset:1024
	global_load_dword v139, v[36:37], off offset:1536
	v_mfma_f32_32x32x16_bf16 v[0:15], v[40:43], v[32:35], v[0:15]
	s_waitcnt vmcnt(56)
	v_cvt_pk_bf16_f32 v60, v140, v141
	v_cvt_pk_bf16_f32 v61, v142, v143
	v_cvt_pk_bf16_f32 v62, v144, v145
	v_cvt_pk_bf16_f32 v63, v146, v147
	global_load_dword v140, v[36:37], off offset:-1920
	global_load_dword v141, v[36:37], off offset:-1408
	global_load_dword v142, v[36:37], off offset:-896
	global_load_dword v143, v[36:37], off offset:-384
	global_load_dword v144, v[36:37], off offset:128
	global_load_dword v145, v[36:37], off offset:640
	global_load_dword v146, v[36:37], off offset:1152
	global_load_dword v147, v[36:37], off offset:1664
	v_mfma_f32_32x32x16_bf16 v[16:31], v[60:63], v[32:35], v[16:31]
	s_waitcnt vmcnt(56)
	v_cvt_pk_bf16_f32 v40, v148, v149
	v_cvt_pk_bf16_f32 v41, v150, v151
	v_cvt_pk_bf16_f32 v42, v152, v153
	v_cvt_pk_bf16_f32 v43, v154, v155
	global_load_dword v148, v[36:37], off offset:-1792
	global_load_dword v149, v[36:37], off offset:-1280
	global_load_dword v150, v[36:37], off offset:-768
	global_load_dword v151, v[36:37], off offset:-256
	global_load_dword v152, v[36:37], off offset:256
	global_load_dword v153, v[36:37], off offset:768
	global_load_dword v154, v[36:37], off offset:1280
	global_load_dword v155, v[36:37], off offset:1792
	v_mfma_f32_32x32x16_bf16 v[64:79], v[40:43], v[32:35], v[64:79]
	s_waitcnt vmcnt(56)
	v_cvt_pk_bf16_f32 v60, v156, v157
	v_cvt_pk_bf16_f32 v61, v158, v159
	v_cvt_pk_bf16_f32 v62, v160, v161
	v_cvt_pk_bf16_f32 v63, v162, v163
	global_load_dword v156, v[36:37], off offset:-1664
	global_load_dword v157, v[36:37], off offset:-1152
	global_load_dword v158, v[36:37], off offset:-640
	global_load_dword v159, v[36:37], off offset:-128
	global_load_dword v160, v[36:37], off offset:384
	global_load_dword v161, v[36:37], off offset:896
	global_load_dword v162, v[36:37], off offset:1408
	global_load_dword v163, v[36:37], off offset:1920
	v_mfma_f32_32x32x16_bf16 v[80:95], v[60:63], v[32:35], v[80:95]
	v_lshl_add_u64 v[36:37], v[36:37], 0, s[28:29]
	ds_read_b128 v[32:35], v131 offset:6144
	s_waitcnt vmcnt(56) lgkmcnt(1)
	v_cvt_pk_bf16_f32 v40, v164, v165
	v_cvt_pk_bf16_f32 v41, v166, v167
	v_cvt_pk_bf16_f32 v42, v168, v169
	v_cvt_pk_bf16_f32 v43, v170, v171
	global_load_dword v164, v[36:37], off offset:-2048
	global_load_dword v165, v[36:37], off offset:-1536
	global_load_dword v166, v[36:37], off offset:-1024
	global_load_dword v167, v[36:37], off offset:-512
	global_load_dword v168, v[36:37], off
	global_load_dword v169, v[36:37], off offset:512
	global_load_dword v170, v[36:37], off offset:1024
	global_load_dword v171, v[36:37], off offset:1536
	v_mfma_f32_32x32x16_bf16 v[0:15], v[40:43], v[104:107], v[0:15]
	s_waitcnt vmcnt(56)
; #define MFMA32(a, b, c) __builtin_amdgcn_mfma_f32_32x32x16_bf16((a), (b), (c), 0, 0, 0)
; __device__ __forceinline__ s16x8 pack8(const float (&x)[8]) { u32x4 p; p.x = pk2(x[0], x[1]); p.y = pk2(x[2], x[3]); p.z = pk2(x[4], x[5]); p.w = pk2(x[6], x[7]); return __builtin_bit_cast(s16x8, p); }
;     __device__ __forceinline__ bf16* U() const { return (bf16*)(ws + WS_U); }
;     __device__ __forceinline__ bf16* DC() const { return (bf16*)(ws + WS_XN); }
; template <bool SAMPLE>
; __device__ __forceinline__ void mout_task(Ctx& C, int l, int unit, int h, int tb, const LAS float* cwl, const LAS float* gainl, LAS float* gsbuf, LAS s16x8* qfl, const bool st) {
;     ...
;                 acc[vb] = MFMA32(pack8(x), qv, acc[vb]); } }
;     } else {
;         const bf16* cp = C.DC() + (size_t)slot * 16384 + (size_t)r * 128 + 8 * hi;
; #pragma unroll 1
;         for (int ks = 0; ks < 8; ++ks) { const s16x8 qv = qfl[ks * 64 + lane];
; #pragma unroll
;             for (int vb = 0; vb < 4; ++vb) acc[vb] = MFMA32(*(const s16x8*)(cp + (size_t)vb * 4096 + 16 * ks), qv, acc[vb]); }
;     }
; #pragma unroll
;     for (int vb = 0; vb < 4; ++vb)
; #pragma unroll
;         for (int i = 0; i < 16; ++i) acc[vb][i] *= winter;
;     float den = 0.f;
;     const int nsb = SAMPLE ? 1 : tb + 1;
; #pragma unroll 1
;     for (int sb = 0; sb < nsb; ++sb) {
;         f32x16 S;
; #pragma unroll
;         for (int i = 0; i < 16; ++i) S[i] = 0.f;
;         const int sl = 32 * sb + r;
;         { s16x8 tk[8];
;           const bf16* kp = C.U() + (grow0 + sl) * UW + C_KM + h * 128 + 8 * hi;
; #pragma unroll
;           for (int ks = 0; ks < 8; ++ks) tk[ks] = *(const s16x8*)(kp + 16 * ks);
	v_cvt_pk_bf16_f32 v60, v172, v173
	v_cvt_pk_bf16_f32 v61, v174, v175
	v_cvt_pk_bf16_f32 v62, v176, v177
	v_cvt_pk_bf16_f32 v63, v178, v179
	global_load_dword v172, v[36:37], off offset:-1920
	global_load_dword v173, v[36:37], off offset:-1408
	global_load_dword v174, v[36:37], off offset:-896
	global_load_dword v175, v[36:37], off offset:-384
	global_load_dword v176, v[36:37], off offset:128
	global_load_dword v177, v[36:37], off offset:640
	global_load_dword v178, v[36:37], off offset:1152
	global_load_dword v179, v[36:37], off offset:1664
	v_mfma_f32_32x32x16_bf16 v[16:31], v[60:63], v[104:107], v[16:31]
	s_waitcnt vmcnt(56)
	v_cvt_pk_bf16_f32 v40, v180, v181
	v_cvt_pk_bf16_f32 v41, v182, v183
	v_cvt_pk_bf16_f32 v42, v184, v47
	v_cvt_pk_bf16_f32 v43, v48, v49
	global_load_dword v180, v[36:37], off offset:-1792
	global_load_dword v181, v[36:37], off offset:-1280
	global_load_dword v182, v[36:37], off offset:-768
	global_load_dword v183, v[36:37], off offset:-256
	global_load_dword v184, v[36:37], off offset:256
	global_load_dword v47, v[36:37], off offset:768
	global_load_dword v48, v[36:37], off offset:1280
	global_load_dword v49, v[36:37], off offset:1792
	v_mfma_f32_32x32x16_bf16 v[64:79], v[40:43], v[104:107], v[64:79]
	s_waitcnt vmcnt(56)
	v_cvt_pk_bf16_f32 v60, v50, v51
	v_cvt_pk_bf16_f32 v61, v52, v53
	v_cvt_pk_bf16_f32 v62, v54, v55
	v_cvt_pk_bf16_f32 v63, v56, v57
	global_load_dword v50, v[36:37], off offset:-1664
	global_load_dword v51, v[36:37], off offset:-1152
	global_load_dword v52, v[36:37], off offset:-640
	global_load_dword v53, v[36:37], off offset:-128
	global_load_dword v54, v[36:37], off offset:384
	global_load_dword v55, v[36:37], off offset:896
	global_load_dword v56, v[36:37], off offset:1408
	global_load_dword v57, v[36:37], off offset:1920
	v_mfma_f32_32x32x16_bf16 v[80:95], v[60:63], v[104:107], v[80:95]
	v_lshl_add_u64 v[36:37], v[36:37], 0, s[28:29]
	ds_read_b128 v[104:107], v131 offset:7168
	s_waitcnt vmcnt(56) lgkmcnt(1)
	v_cvt_pk_bf16_f32 v40, v132, v133
	v_cvt_pk_bf16_f32 v41, v134, v135
	v_cvt_pk_bf16_f32 v42, v136, v137
	v_cvt_pk_bf16_f32 v43, v138, v139
	s_nop 1
	v_mfma_f32_32x32x16_bf16 v[0:15], v[40:43], v[32:35], v[0:15]
	s_waitcnt vmcnt(48)
	v_cvt_pk_bf16_f32 v60, v140, v141
	v_cvt_pk_bf16_f32 v61, v142, v143
	v_cvt_pk_bf16_f32 v62, v144, v145
	v_cvt_pk_bf16_f32 v63, v146, v147
	s_nop 1
	v_mfma_f32_32x32x16_bf16 v[16:31], v[60:63], v[32:35], v[16:31]
	s_waitcnt vmcnt(40)
	v_cvt_pk_bf16_f32 v40, v148, v149
	v_cvt_pk_bf16_f32 v41, v150, v151
	v_cvt_pk_bf16_f32 v42, v152, v153
	v_cvt_pk_bf16_f32 v43, v154, v155
	s_nop 1
	v_mfma_f32_32x32x16_bf16 v[64:79], v[40:43], v[32:35], v[64:79]
	s_waitcnt vmcnt(32)
	v_cvt_pk_bf16_f32 v60, v156, v157
	v_cvt_pk_bf16_f32 v61, v158, v159
	v_cvt_pk_bf16_f32 v62, v160, v161
	v_cvt_pk_bf16_f32 v63, v162, v163
	s_nop 1
	v_mfma_f32_32x32x16_bf16 v[80:95], v[60:63], v[32:35], v[80:95]
	s_waitcnt vmcnt(24) lgkmcnt(0)
	v_cvt_pk_bf16_f32 v40, v164, v165
	v_cvt_pk_bf16_f32 v41, v166, v167
	v_cvt_pk_bf16_f32 v42, v168, v169
	v_cvt_pk_bf16_f32 v43, v170, v171
	s_nop 1
	v_mfma_f32_32x32x16_bf16 v[0:15], v[40:43], v[104:107], v[0:15]
	s_waitcnt vmcnt(16)
	v_cvt_pk_bf16_f32 v60, v172, v173
	v_cvt_pk_bf16_f32 v61, v174, v175
	v_cvt_pk_bf16_f32 v62, v176, v177
	v_cvt_pk_bf16_f32 v63, v178, v179
	s_nop 1
	v_mfma_f32_32x32x16_bf16 v[16:31], v[60:63], v[104:107], v[16:31]
	s_waitcnt vmcnt(8)
	v_cvt_pk_bf16_f32 v40, v180, v181
	v_cvt_pk_bf16_f32 v41, v182, v183
	v_cvt_pk_bf16_f32 v42, v184, v47
	v_cvt_pk_bf16_f32 v43, v48, v49
	s_nop 1
	v_mfma_f32_32x32x16_bf16 v[64:79], v[40:43], v[104:107], v[64:79]
	s_waitcnt vmcnt(0)
	v_cvt_pk_bf16_f32 v60, v50, v51
	v_cvt_pk_bf16_f32 v61, v52, v53
	v_cvt_pk_bf16_f32 v62, v54, v55
	v_cvt_pk_bf16_f32 v63, v56, v57
	s_nop 1
	v_mfma_f32_32x32x16_bf16 v[80:95], v[60:63], v[104:107], v[80:95]
	s_movk_i32 s5, 0x2000
	v_add_f32_e32 v32, v38, v97
	v_sub_f32_e32 v32, v32, v101
	v_mul_f32_e32 v32, 0x3fb8aa3b, v32
	v_exp_f32_e32 v100, v32
	v_lshl_add_u32 v103, v116, 2, s3
	s_mov_b32 s6, 0x3fb8aa3b
	v_cmp_gt_u32_e32 vcc, v192, v129
	v_pk_mul_f32 v[32:33], v[100:101], v[16:17] op_sel_hi:[0,1]
	v_pk_mul_f32 v[16:17], v[100:101], v[64:65] op_sel_hi:[0,1]
	v_or_b32_e32 v64, s4, v192
	v_mul_u32_u24_e32 v64, 0x8400, v64
	v_lshlrev_b32_e32 v64, 1, v64
	v_mov_b32_e32 v65, v193
	v_lshl_add_u64 v[64:65], s[90:91], 0, v[64:65]
	v_pk_mul_f32 v[60:61], v[100:101], v[12:13] op_sel_hi:[0,1]
	v_pk_mul_f32 v[58:59], v[100:101], v[10:11] op_sel_hi:[0,1]
	v_pk_mul_f32 v[56:57], v[100:101], v[8:9] op_sel_hi:[0,1]
	v_pk_mul_f32 v[54:55], v[100:101], v[6:7] op_sel_hi:[0,1]
	v_pk_mul_f32 v[52:53], v[100:101], v[4:5] op_sel_hi:[0,1]
	v_pk_mul_f32 v[50:51], v[100:101], v[2:3] op_sel_hi:[0,1]
	v_pk_mul_f32 v[48:49], v[100:101], v[0:1] op_sel_hi:[0,1]
	v_pk_mul_f32 v[34:35], v[100:101], v[18:19] op_sel_hi:[0,1]
	v_pk_mul_f32 v[18:19], v[100:101], v[66:67] op_sel_hi:[0,1]
	v_pk_mul_f32 v[12:13], v[100:101], v[92:93] op_sel_hi:[0,1]
	v_pk_mul_f32 v[10:11], v[100:101], v[90:91] op_sel_hi:[0,1]
	v_pk_mul_f32 v[8:9], v[100:101], v[88:89] op_sel_hi:[0,1]
	v_pk_mul_f32 v[6:7], v[100:101], v[86:87] op_sel_hi:[0,1]
	v_pk_mul_f32 v[4:5], v[100:101], v[84:85] op_sel_hi:[0,1]
	v_pk_mul_f32 v[2:3], v[100:101], v[82:83] op_sel_hi:[0,1]
	v_pk_mul_f32 v[0:1], v[100:101], v[80:81] op_sel_hi:[0,1]
	v_lshl_add_u64 v[92:93], s[40:41], 1, v[64:65]
	global_load_dwordx4 v[64:67], v[98:99], off offset:3072
	global_load_dwordx4 v[80:83], v[98:99], off offset:3104
	global_load_dwordx4 v[84:87], v[98:99], off offset:3136
	global_load_dwordx4 v[88:91], v[98:99], off offset:3168
	global_load_dwordx4 v[104:107], v[98:99], off offset:3200
; #define LAS __attribute__((address_space(3)))
; __device__ __forceinline__ unsigned pk2(float lo, float hi) { f32x2_t v = {lo, hi}; bf16x2_t b = __builtin_convertvector(v, bf16x2_t); return __builtin_bit_cast(unsigned, b); }
; #define MFMA32(a, b, c) __builtin_amdgcn_mfma_f32_32x32x16_bf16((a), (b), (c), 0, 0, 0)
;     __device__ __forceinline__ bf16* KVt() const { return (bf16*)(ws + WS_KVT); }
; template <bool SAMPLE>
; __device__ __forceinline__ void mout_task(Ctx& C, int l, int unit, int h, int tb, const LAS float* cwl, const LAS float* gainl, LAS float* gsbuf, LAS s16x8* qfl, const bool st) {
;     ...
;           for (int ks = 0; ks < 8; ++ks) tk[ks] = *(const s16x8*)(kp + 16 * ks);
; #pragma unroll
;           for (int ks = 0; ks < 8; ++ks) S = MFMA32(tk[ks], qfl[ks * 64 + lane], S); }
;         const float e0 = (bt - mt) * LOG2E;
; #pragma unroll
;         for (int i4 = 0; i4 < 4; ++i4) { const f32x4 gs = *(const LAS f32x4*)(gsbuf + 32 * sb + 8 * i4 + 4 * hi);
; #pragma unroll
;             for (int e = 0; e < 4; ++e) { const int sidx = 32 * sb + 8 * i4 + 4 * hi + e;
;                 const float wv = (sidx <= tl) ? __builtin_amdgcn_exp2f(e0 + gs[e] * LOG2E) : 0.f;
;                 S[4 * i4 + e] *= wv; den += S[4 * i4 + e]; } }
; #pragma unroll
;         for (int s2 = 0; s2 < 2; ++s2) { u32x4 w; w.x = pk2(S[8 * s2], S[8 * s2 + 1]); w.y = pk2(S[8 * s2 + 2], S[8 * s2 + 3]); w.z = pk2(S[8 * s2 + 4], S[8 * s2 + 5]); w.w = pk2(S[8 * s2 + 6], S[8 * s2 + 7]);
;             const s16x8 pf = __builtin_bit_cast(s16x8, w);
;             const bf16* vp0 = C.KVt() + (size_t)(R_VM + h * 128 + r) * MT + grow0 + 32 * sb + 16 * s2 + 4 * hi;
; #pragma unroll
;             for (int vb = 0; vb < 4; ++vb) { const bf16* vp = vp0 + (size_t)(32 * vb) * MT;
;                 const u32x2 a = *(const u32x2*)vp, bq = *(const u32x2*)(vp + 8); u32x4 vw; vw.x = a.x; vw.y = a.y; vw.z = bq.x; vw.w = bq.y;
	global_load_dwordx4 v[108:111], v[98:99], off offset:3232
	global_load_dwordx4 v[116:119], v[98:99], off offset:3264
	global_load_dwordx4 v[120:123], v[98:99], off offset:3296
	v_pk_mul_f32 v[38:39], v[100:101], v[22:23] op_sel_hi:[0,1]
	v_pk_mul_f32 v[36:37], v[100:101], v[20:21] op_sel_hi:[0,1]
	v_pk_mul_f32 v[22:23], v[100:101], v[70:71] op_sel_hi:[0,1]
	v_pk_mul_f32 v[20:21], v[100:101], v[68:69] op_sel_hi:[0,1]
	ds_read_b128 v[68:71], v127 offset:32768
	ds_read_b128 v[130:133], v127 offset:33792
	v_pk_mul_f32 v[46:47], v[100:101], v[30:31] op_sel_hi:[0,1]
	v_pk_mul_f32 v[44:45], v[100:101], v[28:29] op_sel_hi:[0,1]
	v_pk_mul_f32 v[42:43], v[100:101], v[26:27] op_sel_hi:[0,1]
	v_pk_mul_f32 v[40:41], v[100:101], v[24:25] op_sel_hi:[0,1]
	v_pk_mul_f32 v[30:31], v[100:101], v[78:79] op_sel_hi:[0,1]
	v_pk_mul_f32 v[28:29], v[100:101], v[76:77] op_sel_hi:[0,1]
	v_pk_mul_f32 v[26:27], v[100:101], v[74:75] op_sel_hi:[0,1]
	v_pk_mul_f32 v[24:25], v[100:101], v[72:73] op_sel_hi:[0,1]
	v_pk_mul_f32 v[62:63], v[100:101], v[14:15] op_sel_hi:[0,1]
	v_pk_mul_f32 v[14:15], v[100:101], v[94:95] op_sel_hi:[0,1]
	v_sub_f32_e32 v94, v97, v101
	v_or_b32_e32 v97, 3, v129
	v_or_b32_e32 v113, 17, v129
	v_or_b32_e32 v115, 19, v129
	s_mov_b32 s5, 0x14a00000
	ds_bpermute_b32 v102, v125, v96
	s_lshl_b32 s78, s4, 1
	s_lshl_b32 s4, s4, 2
	s_add_i32 s4, s4, 0
	s_waitcnt vmcnt(7) lgkmcnt(2)
	v_mfma_f32_32x32x16_bf16 v[64:79], v[64:67], v[68:71], 0
	s_waitcnt vmcnt(6) lgkmcnt(1)
	v_mfma_f32_32x32x16_bf16 v[64:79], v[80:83], v[130:133], v[64:79]
	ds_read_b128 v[80:83], v127 offset:34816
	s_waitcnt vmcnt(5) lgkmcnt(0)
	v_mfma_f32_32x32x16_bf16 v[64:79], v[84:87], v[80:83], v[64:79]
	ds_read_b128 v[80:83], v127 offset:35840
	s_waitcnt vmcnt(4) lgkmcnt(0)
	v_mfma_f32_32x32x16_bf16 v[64:79], v[88:91], v[80:83], v[64:79]
	ds_read_b128 v[80:83], v127 offset:36864
	s_waitcnt vmcnt(3) lgkmcnt(0)
	v_mfma_f32_32x32x16_bf16 v[64:79], v[104:107], v[80:83], v[64:79]
	ds_read_b128 v[80:83], v127 offset:37888
	s_waitcnt vmcnt(2) lgkmcnt(0)
	v_mfma_f32_32x32x16_bf16 v[64:79], v[108:111], v[80:83], v[64:79]
	ds_read_b128 v[80:83], v127 offset:38912
	v_or_b32_e32 v108, 9, v129
	v_or_b32_e32 v109, 8, v129
	v_or_b32_e32 v110, 11, v129
	v_or_b32_e32 v111, 10, v129
	s_waitcnt vmcnt(1) lgkmcnt(0)
	v_mfma_f32_32x32x16_bf16 v[64:79], v[116:119], v[80:83], v[64:79]
	ds_read_b128 v[80:83], v127 offset:39936
	v_or_b32_e32 v116, 18, v129
	v_or_b32_e32 v117, 25, v129
	v_or_b32_e32 v118, 24, v129
	v_or_b32_e32 v119, 27, v129
	s_waitcnt vmcnt(0) lgkmcnt(0)
	v_mfma_f32_32x32x16_bf16 v[64:79], v[120:123], v[80:83], v[64:79]
	v_lshlrev_b32_e32 v130, 1, v129
	v_mov_b32_e32 v131, 0
	v_lshl_add_u64 v[132:133], v[92:93], 0, v[130:131]
	s_mov_b64 s[72:73], 0x14a00000
	v_lshl_add_u64 v[134:135], v[132:133], 0, s[72:73]
	s_mov_b64 s[72:73], 0x14c10000
	v_lshl_add_u64 v[136:137], v[132:133], 0, s[72:73]
	s_mov_b64 s[72:73], 0x14e20000
	v_lshl_add_u64 v[138:139], v[132:133], 0, s[72:73]
	s_mov_b64 s[72:73], 0x15030000
	v_lshl_add_u64 v[140:141], v[132:133], 0, s[72:73]
	global_load_dwordx2 v[144:145], v[134:135], off
	global_load_dwordx2 v[146:147], v[134:135], off offset:16
	global_load_dwordx2 v[148:149], v[136:137], off
	global_load_dwordx2 v[150:151], v[136:137], off offset:16
	global_load_dwordx2 v[152:153], v[138:139], off
	global_load_dwordx2 v[154:155], v[138:139], off offset:16
	global_load_dwordx2 v[156:157], v[140:141], off
	global_load_dwordx2 v[158:159], v[140:141], off offset:16
	global_load_dwordx2 v[160:161], v[134:135], off offset:32
	global_load_dwordx2 v[162:163], v[134:135], off offset:48
	global_load_dwordx2 v[164:165], v[136:137], off offset:32
	global_load_dwordx2 v[166:167], v[136:137], off offset:48
	global_load_dwordx2 v[168:169], v[138:139], off offset:32
	global_load_dwordx2 v[170:171], v[138:139], off offset:48
	global_load_dwordx2 v[172:173], v[140:141], off offset:32
	global_load_dwordx2 v[174:175], v[140:141], off offset:48
	v_sub_u32_e32 v80, v103, v114
	ds_read_b128 v[104:107], v80 offset:22528
	ds_read_b128 v[88:91], v80 offset:22560
	ds_read_b128 v[84:87], v80 offset:22592
	ds_read_b128 v[80:83], v80 offset:22624
	v_or_b32_e32 v103, 2, v129
	v_or_b32_e32 v114, 16, v129
	v_or_b32_e32 v120, 26, v129
	s_waitcnt lgkmcnt(0)
; #define LAS __attribute__((address_space(3)))
; __device__ __forceinline__ unsigned pk2(float lo, float hi) { f32x2_t v = {lo, hi}; bf16x2_t b = __builtin_convertvector(v, bf16x2_t); return __builtin_bit_cast(unsigned, b); }
; __device__ __forceinline__ float fexp(float x) { return __builtin_amdgcn_exp2f(x * LOG2E); }
; #define MFMA32(a, b, c) __builtin_amdgcn_mfma_f32_32x32x16_bf16((a), (b), (c), 0, 0, 0)
;     __device__ __forceinline__ bf16* KVt() const { return (bf16*)(ws + WS_KVT); }
; template <bool SAMPLE>
; __device__ __forceinline__ void mout_task(Ctx& C, int l, int unit, int h, int tb, const LAS float* cwl, const LAS float* gainl, LAS float* gsbuf, LAS s16x8* qfl, const bool st) {
;     ...
;         const float e0 = (bt - mt) * LOG2E;
; #pragma unroll
;         for (int i4 = 0; i4 < 4; ++i4) { const f32x4 gs = *(const LAS f32x4*)(gsbuf + 32 * sb + 8 * i4 + 4 * hi);
; #pragma unroll
;             for (int e = 0; e < 4; ++e) { const int sidx = 32 * sb + 8 * i4 + 4 * hi + e;
;                 const float wv = (sidx <= tl) ? __builtin_amdgcn_exp2f(e0 + gs[e] * LOG2E) : 0.f;
;                 S[4 * i4 + e] *= wv; den += S[4 * i4 + e]; } }
; #pragma unroll
;         for (int s2 = 0; s2 < 2; ++s2) { u32x4 w; w.x = pk2(S[8 * s2], S[8 * s2 + 1]); w.y = pk2(S[8 * s2 + 2], S[8 * s2 + 3]); w.z = pk2(S[8 * s2 + 4], S[8 * s2 + 5]); w.w = pk2(S[8 * s2 + 6], S[8 * s2 + 7]);
;             const s16x8 pf = __builtin_bit_cast(s16x8, w);
;             const bf16* vp0 = C.KVt() + (size_t)(R_VM + h * 128 + r) * MT + grow0 + 32 * sb + 16 * s2 + 4 * hi;
; #pragma unroll
;             for (int vb = 0; vb < 4; ++vb) { const bf16* vp = vp0 + (size_t)(32 * vb) * MT;
;                 const u32x2 a = *(const u32x2*)vp, bq = *(const u32x2*)(vp + 8); u32x4 vw; vw.x = a.x; vw.y = a.y; vw.z = bq.x; vw.w = bq.y;
;                 acc[vb] = MFMA32(__builtin_bit_cast(s16x8, vw), pf, acc[vb]); } }
;     }
;     den += __shfl_xor(den, 32);
;     den += winter * qn;
;     const float inv = __builtin_amdgcn_rcpf(fmaxf(fabsf(den), fexp(-mt)));
	v_mov_b32_e32 v95, v83
	v_pk_mul_f32 v[94:95], v[94:95], s[6:7] op_sel_hi:[1,0]
	s_mov_b64 s[6:7], 0x14a00000
	v_fmamk_f32 v98, v105, 0x3fb8aa3b, v94
	v_fmamk_f32 v83, v104, 0x3fb8aa3b, v94
	v_exp_f32_e32 v98, v98
	v_exp_f32_e32 v83, v83
	v_cndmask_b32_e32 v99, 0, v98, vcc
	v_cmp_le_u32_e32 vcc, v129, v192
	s_nop 1
	v_cndmask_b32_e32 v98, 0, v83, vcc
	v_pk_mul_f32 v[64:65], v[64:65], v[98:99]
	v_fmamk_f32 v99, v107, 0x3fb8aa3b, v94
	v_fmamk_f32 v98, v106, 0x3fb8aa3b, v94
	v_exp_f32_e32 v99, v99
	v_exp_f32_e32 v98, v98
	v_cmp_le_u32_e32 vcc, v97, v192
	v_add_f32_e32 v83, 0, v64
	v_add_f32_e32 v83, v65, v83
	v_cndmask_b32_e32 v99, 0, v99, vcc
	v_cmp_le_u32_e32 vcc, v103, v192
	s_nop 1
	v_cndmask_b32_e32 v98, 0, v98, vcc
	v_pk_mul_f32 v[98:99], v[66:67], v[98:99]
	v_fmamk_f32 v67, v89, 0x3fb8aa3b, v94
	v_add_f32_e32 v66, v98, v83
	v_add_f32_e32 v83, v99, v66
	v_fmamk_f32 v66, v88, 0x3fb8aa3b, v94
	v_exp_f32_e32 v67, v67
	v_exp_f32_e32 v66, v66
	v_cmp_le_u32_e32 vcc, v108, v192
	s_nop 1
	v_cndmask_b32_e32 v67, 0, v67, vcc
	v_cmp_le_u32_e32 vcc, v109, v192
	s_nop 1
	v_cndmask_b32_e32 v66, 0, v66, vcc
	v_pk_mul_f32 v[88:89], v[68:69], v[66:67]
	v_fmamk_f32 v67, v91, 0x3fb8aa3b, v94
	v_add_f32_e32 v66, v88, v83
	v_add_f32_e32 v68, v89, v66
	v_fmamk_f32 v66, v90, 0x3fb8aa3b, v94
	v_exp_f32_e32 v67, v67
	v_exp_f32_e32 v66, v66
	v_cmp_le_u32_e32 vcc, v110, v192
	s_nop 1
	v_cndmask_b32_e32 v67, 0, v67, vcc
	v_cmp_le_u32_e32 vcc, v111, v192
	s_nop 1
	v_cndmask_b32_e32 v66, 0, v66, vcc
	v_pk_mul_f32 v[90:91], v[70:71], v[66:67]
	v_fmamk_f32 v67, v85, 0x3fb8aa3b, v94
	v_add_f32_e32 v66, v90, v68
	v_add_f32_e32 v70, v91, v66
	v_fmamk_f32 v66, v84, 0x3fb8aa3b, v94
	v_exp_f32_e32 v67, v67
	v_exp_f32_e32 v66, v66
	v_cmp_le_u32_e32 vcc, v113, v192
	v_add_f32_e32 v71, v94, v95
	v_exp_f32_e32 v71, v71
	v_cndmask_b32_e32 v67, 0, v67, vcc
	v_cmp_le_u32_e32 vcc, v114, v192
	s_nop 1
	v_cndmask_b32_e32 v66, 0, v66, vcc
	v_pk_mul_f32 v[68:69], v[72:73], v[66:67]
	v_fmamk_f32 v67, v87, 0x3fb8aa3b, v94
	v_add_f32_e32 v66, v68, v70
	v_add_f32_e32 v70, v69, v66
	v_fmamk_f32 v66, v86, 0x3fb8aa3b, v94
	v_exp_f32_e32 v67, v67
	v_exp_f32_e32 v66, v66
	v_cmp_le_u32_e32 vcc, v115, v192
	s_nop 1
	v_cndmask_b32_e32 v67, 0, v67, vcc
	v_cmp_le_u32_e32 vcc, v116, v192
	s_nop 1
	v_cndmask_b32_e32 v66, 0, v66, vcc
	v_pk_mul_f32 v[72:73], v[74:75], v[66:67]
	v_fmamk_f32 v67, v81, 0x3fb8aa3b, v94
	v_add_f32_e32 v66, v72, v70
	v_add_f32_e32 v97, v73, v66
	v_fmamk_f32 v66, v80, 0x3fb8aa3b, v94
	v_exp_f32_e32 v67, v67
	v_exp_f32_e32 v66, v66
	v_cmp_le_u32_e32 vcc, v117, v192
	v_fmamk_f32 v70, v82, 0x3fb8aa3b, v94
	v_exp_f32_e32 v70, v70
	v_cndmask_b32_e32 v67, 0, v67, vcc
	v_cmp_le_u32_e32 vcc, v118, v192
	v_cvt_pk_bf16_f32 v74, v64, v65
	v_cvt_pk_bf16_f32 v75, v98, v99
	v_cndmask_b32_e32 v66, 0, v66, vcc
	v_cmp_le_u32_e32 vcc, v119, v192
	v_pk_mul_f32 v[66:67], v[76:77], v[66:67]
	v_cvt_pk_bf16_f32 v76, v88, v89
	v_cndmask_b32_e32 v71, 0, v71, vcc
	v_cmp_le_u32_e32 vcc, v120, v192
	v_lshlrev_b32_e32 v192, 1, v129
	v_lshl_add_u64 v[82:83], v[92:93], 0, v[192:193]
	v_cndmask_b32_e32 v70, 0, v70, vcc
	v_add_co_u32_e32 v64, vcc, s5, v82
	v_pk_mul_f32 v[70:71], v[78:79], v[70:71]
	s_nop 0
	v_addc_co_u32_e32 v65, vcc, 0, v83, vcc
	v_lshl_add_u64 v[84:85], v[82:83], 0, s[6:7]
	s_mov_b32 s5, 0x14c10000
	v_add_co_u32_e32 v64, vcc, s5, v82
	v_cvt_pk_bf16_f32 v77, v90, v91
	s_nop 0
	v_addc_co_u32_e32 v65, vcc, 0, v83, vcc
	s_waitcnt vmcnt(14)
	v_mfma_f32_32x32x16_bf16 v[48:63], v[144:147], v[74:77], v[48:63]
	s_mov_b32 s5, 0x14e20000
	v_add_co_u32_e32 v86, vcc, s5, v82
	s_mov_b32 s5, 0x15030000
	s_nop 0
	v_addc_co_u32_e32 v87, vcc, 0, v83, vcc
	s_waitcnt vmcnt(12)
	v_mfma_f32_32x32x16_bf16 v[32:47], v[148:151], v[74:77], v[32:47]
	v_add_co_u32_e32 v82, vcc, s5, v82
	s_nop 1
	v_addc_co_u32_e32 v83, vcc, 0, v83, vcc
	s_waitcnt vmcnt(10)
	v_mfma_f32_32x32x16_bf16 v[16:31], v[152:155], v[74:77], v[16:31]
	s_waitcnt vmcnt(8)
	v_mfma_f32_32x32x16_bf16 v[0:15], v[156:159], v[74:77], v[0:15]
	v_cvt_pk_bf16_f32 v74, v68, v69
	v_cvt_pk_bf16_f32 v75, v72, v73
	v_cvt_pk_bf16_f32 v76, v66, v67
	v_cvt_pk_bf16_f32 v77, v70, v71
	s_waitcnt vmcnt(6)
	s_nop 0
	v_mfma_f32_32x32x16_bf16 v[48:63], v[160:163], v[74:77], v[48:63]
	v_add_f32_e32 v64, v66, v97
	v_add_f32_e32 v64, v67, v64
	v_add_f32_e32 v64, v70, v64
	v_add_f32_e32 v97, v71, v64
	ds_bpermute_b32 v103, v125, v97
	s_waitcnt lgkmcnt(0)
	v_pk_add_f32 v[64:65], v[96:97], v[102:103]
	s_waitcnt vmcnt(4)
	v_mfma_f32_32x32x16_bf16 v[32:47], v[164:167], v[74:77], v[32:47]
	v_fmac_f32_e32 v65, v100, v64
	v_mul_f32_e32 v64, 0xbfb8aa3b, v101
	v_exp_f32_e32 v64, v64
	s_nop 0
	v_max_f32_e64 v64, |v65|, v64
	s_waitcnt vmcnt(2)
	v_mfma_f32_32x32x16_bf16 v[16:31], v[168:171], v[74:77], v[16:31]
	s_waitcnt vmcnt(0)
; #define LAS __attribute__((address_space(3)))
; __device__ __forceinline__ float fexp(float x) { return __builtin_amdgcn_exp2f(x * LOG2E); }
; #define MFMA32(a, b, c) __builtin_amdgcn_mfma_f32_32x32x16_bf16((a), (b), (c), 0, 0, 0)
;     __device__ __forceinline__ bf16* U() const { return (bf16*)(ws + WS_U); }
; template <bool SAMPLE>
; __device__ __forceinline__ void mout_task(Ctx& C, int l, int unit, int h, int tb, const LAS float* cwl, const LAS float* gainl, LAS float* gsbuf, LAS s16x8* qfl, const bool st) {
;     ...
;             for (int vb = 0; vb < 4; ++vb) { const bf16* vp = vp0 + (size_t)(32 * vb) * MT;
;                 const u32x2 a = *(const u32x2*)vp, bq = *(const u32x2*)(vp + 8); u32x4 vw; vw.x = a.x; vw.y = a.y; vw.z = bq.x; vw.w = bq.y;
;                 acc[vb] = MFMA32(__builtin_bit_cast(s16x8, vw), pf, acc[vb]); } }
;     }
;     den += __shfl_xor(den, 32);
;     den += winter * qn;
;     const float inv = __builtin_amdgcn_rcpf(fmaxf(fabsf(den), fexp(-mt)));
;     float ss = 0.f;
; #pragma unroll
;     for (int vb = 0; vb < 4; ++vb)
; #pragma unroll
;         for (int i = 0; i < 16; ++i) { acc[vb][i] *= inv; ss += acc[vb][i] * acc[vb][i]; }
;     ss += __shfl_xor(ss, 32);
;     const float rn = rsqrtf(ss * (1.f / 128.f) + EPS);
;     int lane2 = lane; asm volatile("" : "+v"(lane2));
;     const int hi2 = lane2 >> 5;
;     bf16* orow = C.U() + (grow0 + 32 * tb + (lane2 & 31)) * UW + C_OM + h * 128;
; #pragma unroll
;     for (int vb = 0; vb < 4; ++vb)
; #pragma unroll
;         for (int i4 = 0; i4 < 4; ++i4) { const int v0 = 32 * vb + 8 * i4 + 4 * hi2;
;             const u32x2 ow = *(const u32x2*)(orow + v0); const f32x4 gn = *(const LAS f32x4*)(gainl + h * 128 + v0);
	v_mfma_f32_32x32x16_bf16 v[0:15], v[172:175], v[74:77], v[0:15]
	v_rcp_f32_e32 v80, v64
	s_nop 10
	v_pk_mul_f32 v[72:73], v[10:11], v[80:81] op_sel_hi:[1,0]
	v_pk_mul_f32 v[68:69], v[12:13], v[80:81] op_sel_hi:[1,0]
	v_and_or_b32 v12, v112, 31, s40
	v_mov_b64_e32 v[10:11], s[90:91]
	v_mad_u64_u32 v[10:11], s[6:7], v12, s61, v[10:11]
	v_ashrrev_i32_e32 v12, 3, v112
	v_mad_i32_i24 v11, s41, v221, v11
	v_and_b32_e32 v12, -4, v12
	v_lshl_add_u64 v[10:11], v[10:11], 0, s[78:79]
	v_ashrrev_i32_e32 v13, 31, v12
	v_lshl_add_u64 v[10:11], v[12:13], 1, v[10:11]
	s_mov_b64 s[6:7], 0x1000
	v_add_co_u32_e32 v82, vcc, s60, v10
	v_pk_mul_f32 v[14:15], v[14:15], v[80:81] op_sel_hi:[1,0]
	v_lshl_add_u64 v[70:71], v[10:11], 0, s[6:7]
	v_addc_co_u32_e32 v83, vcc, 0, v11, vcc
	v_lshl_add_u32 v81, v12, 2, s4
	global_load_dwordx2 v[86:87], v[82:83], off
	ds_read_b128 v[64:67], v81 offset:20480
	ds_read_b128 v[10:13], v81 offset:20512
	v_pk_mul_f32 v[90:91], v[48:49], v[80:81] op_sel_hi:[1,0]
	global_load_dwordx2 v[48:49], v[70:71], off offset:16
	global_load_dwordx2 v[116:117], v[70:71], off offset:48
	v_pk_mul_f32 v[102:103], v[52:53], v[80:81] op_sel_hi:[1,0]
	global_load_dwordx2 v[52:53], v[70:71], off offset:32
	v_pk_mul_f32 v[88:89], v[50:51], v[80:81] op_sel_hi:[1,0]
	v_pk_mul_f32 v[94:95], v[90:91], v[90:91]
	v_pk_mul_f32 v[92:93], v[88:89], v[88:89]
	v_pk_mul_f32 v[100:101], v[54:55], v[80:81] op_sel_hi:[1,0]
	v_pk_mul_f32 v[58:59], v[58:59], v[80:81] op_sel_hi:[1,0]
	v_pk_mul_f32 v[56:57], v[56:57], v[80:81] op_sel_hi:[1,0]
	v_pk_mul_f32 v[126:127], v[62:63], v[80:81] op_sel_hi:[1,0]
	v_pk_mul_f32 v[130:131], v[60:61], v[80:81] op_sel_hi:[1,0]
	v_pk_mul_f32 v[134:135], v[34:35], v[80:81] op_sel_hi:[1,0]
	v_pk_mul_f32 v[138:139], v[32:33], v[80:81] op_sel_hi:[1,0]
	v_pk_mul_f32 v[60:61], v[42:43], v[80:81] op_sel_hi:[1,0]
	v_pk_mul_f32 v[62:63], v[40:41], v[80:81] op_sel_hi:[1,0]
	v_pk_mul_f32 v[46:47], v[46:47], v[80:81] op_sel_hi:[1,0]
	v_pk_mul_f32 v[44:45], v[44:45], v[80:81] op_sel_hi:[1,0]
	v_pk_mul_f32 v[40:41], v[18:19], v[80:81] op_sel_hi:[1,0]
	v_pk_mul_f32 v[42:43], v[16:17], v[80:81] op_sel_hi:[1,0]
	v_pk_mul_f32 v[32:33], v[26:27], v[80:81] op_sel_hi:[1,0]
	v_pk_mul_f32 v[34:35], v[24:25], v[80:81] op_sel_hi:[1,0]
	v_pk_mul_f32 v[24:25], v[30:31], v[80:81] op_sel_hi:[1,0]
	v_pk_mul_f32 v[26:27], v[28:29], v[80:81] op_sel_hi:[1,0]
	v_pk_mul_f32 v[16:17], v[6:7], v[80:81] op_sel_hi:[1,0]
	v_pk_mul_f32 v[18:19], v[4:5], v[80:81] op_sel_hi:[1,0]
	v_pk_mul_f32 v[6:7], v[8:9], v[80:81] op_sel_hi:[1,0]
	v_pk_mul_f32 v[106:107], v[102:103], v[102:103]
	v_pk_mul_f32 v[104:105], v[100:101], v[100:101]
	v_pk_mul_f32 v[114:115], v[56:57], v[56:57]
	v_pk_mul_f32 v[112:113], v[58:59], v[58:59]
	v_pk_mul_f32 v[132:133], v[130:131], v[130:131]
	v_pk_mul_f32 v[128:129], v[126:127], v[126:127]
	v_pk_mul_f32 v[140:141], v[138:139], v[138:139]
	v_pk_mul_f32 v[136:137], v[134:135], v[134:135]
	v_pk_mul_f32 v[148:149], v[62:63], v[62:63]
	v_pk_mul_f32 v[146:147], v[60:61], v[60:61]
	v_pk_mul_f32 v[152:153], v[44:45], v[44:45]
	v_pk_mul_f32 v[150:151], v[46:47], v[46:47]
	v_pk_mul_f32 v[156:157], v[42:43], v[42:43]
	v_pk_mul_f32 v[154:155], v[40:41], v[40:41]
	v_pk_mul_f32 v[164:165], v[34:35], v[34:35]
	v_pk_mul_f32 v[162:163], v[32:33], v[32:33]
	v_pk_mul_f32 v[28:29], v[26:27], v[26:27]
	v_pk_mul_f32 v[30:31], v[24:25], v[24:25]
	v_pk_mul_f32 v[4:5], v[18:19], v[18:19]
	v_pk_mul_f32 v[166:167], v[16:17], v[16:17]
	v_pk_mul_f32 v[8:9], v[6:7], v[6:7]
	v_pk_mul_f32 v[74:75], v[72:73], v[72:73]
	v_pk_mul_f32 v[76:77], v[68:69], v[68:69]
	v_pk_mul_f32 v[78:79], v[14:15], v[14:15]
	s_waitcnt vmcnt(3)
	v_lshlrev_b32_e32 v84, 16, v86
	v_and_b32_e32 v85, 0xffff0000, v86
	v_lshlrev_b32_e32 v86, 16, v87
	s_waitcnt vmcnt(2)
	v_lshlrev_b32_e32 v50, 16, v48
	s_waitcnt vmcnt(1)
	v_lshlrev_b32_e32 v118, 16, v116
	v_and_b32_e32 v116, 0xffff0000, v116
	v_mul_f32_e32 v116, 0xbfb8aa3b, v116
	v_exp_f32_e32 v116, v116
	v_mul_f32_e32 v118, 0xbfb8aa3b, v118
	v_exp_f32_e32 v118, v118
	v_and_b32_e32 v48, 0xffff0000, v48
	v_add_f32_e32 v116, 1.0, v116
	v_rcp_f32_e32 v121, v116
	v_lshlrev_b32_e32 v116, 16, v117
	v_mul_f32_e32 v116, 0xbfb8aa3b, v116
	v_exp_f32_e32 v116, v116
	v_add_f32_e32 v118, 1.0, v118
	v_rcp_f32_e32 v120, v118
	v_pk_mul_f32 v[118:119], v[36:37], v[80:81] op_sel_hi:[1,0]
	v_add_f32_e32 v116, 1.0, v116
	v_rcp_f32_e32 v122, v116
	v_and_b32_e32 v116, 0xffff0000, v117
	v_mul_f32_e32 v116, 0xbfb8aa3b, v116
	v_exp_f32_e32 v116, v116
	v_pk_mul_f32 v[36:37], v[22:23], v[80:81] op_sel_hi:[1,0]
	v_pk_mul_f32 v[22:23], v[0:1], v[80:81] op_sel_hi:[1,0]
	v_pk_mul_f32 v[144:145], v[118:119], v[118:119]
	v_add_f32_e32 v116, 1.0, v116
	v_rcp_f32_e32 v123, v116
	v_pk_mul_f32 v[116:117], v[38:39], v[80:81] op_sel_hi:[1,0]
	v_pk_mul_f32 v[38:39], v[20:21], v[80:81] op_sel_hi:[1,0]
	v_pk_mul_f32 v[20:21], v[2:3], v[80:81] op_sel_hi:[1,0]
	v_add_f32_e32 v80, v94, v95
	v_add_f32_e32 v80, v92, v80
	v_add_f32_e32 v80, v93, v80
	v_add_f32_e32 v80, v106, v80
	v_add_f32_e32 v80, v107, v80
	v_add_f32_e32 v80, v104, v80
	v_add_f32_e32 v80, v105, v80
	v_add_f32_e32 v80, v114, v80
	v_add_f32_e32 v80, v115, v80
	v_add_f32_e32 v80, v112, v80
	v_add_f32_e32 v80, v113, v80
	v_add_f32_e32 v80, v132, v80
	v_add_f32_e32 v80, v133, v80
	v_add_f32_e32 v80, v128, v80
	v_add_f32_e32 v80, v129, v80
	v_add_f32_e32 v80, v140, v80
	v_add_f32_e32 v80, v141, v80
	v_add_f32_e32 v80, v136, v80
	v_add_f32_e32 v80, v137, v80
	v_add_f32_e32 v80, v144, v80
	v_pk_mul_f32 v[142:143], v[116:117], v[116:117]
	v_add_f32_e32 v80, v145, v80
	v_add_f32_e32 v80, v142, v80
	v_add_f32_e32 v80, v143, v80
	v_add_f32_e32 v80, v148, v80
	v_add_f32_e32 v80, v149, v80
	v_add_f32_e32 v80, v146, v80
	v_add_f32_e32 v80, v147, v80
	v_add_f32_e32 v80, v152, v80
	v_add_f32_e32 v80, v153, v80
	v_add_f32_e32 v80, v150, v80
	v_add_f32_e32 v80, v151, v80
	v_add_f32_e32 v80, v156, v80
	v_add_f32_e32 v80, v157, v80
	v_add_f32_e32 v80, v154, v80
	v_pk_mul_f32 v[160:161], v[38:39], v[38:39]
	v_add_f32_e32 v80, v155, v80
	v_add_f32_e32 v80, v160, v80
	v_pk_mul_f32 v[158:159], v[36:37], v[36:37]
	v_add_f32_e32 v80, v161, v80
	v_add_f32_e32 v80, v158, v80
	v_add_f32_e32 v80, v159, v80
	v_add_f32_e32 v80, v164, v80
	v_add_f32_e32 v80, v165, v80
	v_add_f32_e32 v80, v162, v80
	v_add_f32_e32 v80, v163, v80
	v_add_f32_e32 v28, v28, v80
	v_add_f32_e32 v28, v29, v28
	v_add_f32_e32 v28, v30, v28
	v_pk_mul_f32 v[0:1], v[22:23], v[22:23]
	v_add_f32_e32 v28, v31, v28
	v_add_f32_e32 v0, v0, v28
	v_pk_mul_f32 v[2:3], v[20:21], v[20:21]
	v_add_f32_e32 v0, v1, v0
	v_add_f32_e32 v0, v2, v0
	v_add_f32_e32 v0, v3, v0
	v_add_f32_e32 v0, v4, v0
	v_add_f32_e32 v0, v5, v0
	v_add_f32_e32 v0, v166, v0
	v_add_f32_e32 v0, v167, v0
	v_add_f32_e32 v0, v8, v0
	v_add_f32_e32 v0, v9, v0
	v_add_f32_e32 v0, v74, v0
	v_add_f32_e32 v0, v75, v0
	v_add_f32_e32 v0, v76, v0
	v_mul_f32_e32 v48, 0xbfb8aa3b, v48
	v_add_f32_e32 v0, v77, v0
	v_exp_f32_e32 v48, v48
	v_add_f32_e32 v0, v78, v0
	v_add_f32_e32 v0, v79, v0
	s_waitcnt vmcnt(0)
; #define LAS __attribute__((address_space(3)))
; __device__ __forceinline__ unsigned pk2(float lo, float hi) { f32x2_t v = {lo, hi}; bf16x2_t b = __builtin_convertvector(v, bf16x2_t); return __builtin_bit_cast(unsigned, b); }
; __device__ __forceinline__ float bflo(unsigned w) { return __uint_as_float(w << 16); }
; __device__ __forceinline__ float bfhi(unsigned w) { return __uint_as_float(w & 0xffff0000u); }
; __device__ __forceinline__ float sigmoidf_(float x) { return __builtin_amdgcn_rcpf(1.f + fexp(-x)); }
;     __device__ __forceinline__ bf16* U() const { return (bf16*)(ws + WS_U); }
; template <bool SAMPLE>
; __device__ __forceinline__ void mout_task(Ctx& C, int l, int unit, int h, int tb, const LAS float* cwl, const LAS float* gainl, LAS float* gsbuf, LAS s16x8* qfl, const bool st) {
;     ...
;     ss += __shfl_xor(ss, 32);
;     const float rn = rsqrtf(ss * (1.f / 128.f) + EPS);
;     int lane2 = lane; asm volatile("" : "+v"(lane2));
;     const int hi2 = lane2 >> 5;
;     bf16* orow = C.U() + (grow0 + 32 * tb + (lane2 & 31)) * UW + C_OM + h * 128;
; #pragma unroll
;     for (int vb = 0; vb < 4; ++vb)
; #pragma unroll
;         for (int i4 = 0; i4 < 4; ++i4) { const int v0 = 32 * vb + 8 * i4 + 4 * hi2;
;             const u32x2 ow = *(const u32x2*)(orow + v0); const f32x4 gn = *(const LAS f32x4*)(gainl + h * 128 + v0);
;             const float y0 = acc[vb][4 * i4] * rn * gn[0] * sigmoidf_(bflo(ow.x)), y1 = acc[vb][4 * i4 + 1] * rn * gn[1] * sigmoidf_(bfhi(ow.x));
;             const float y2 = acc[vb][4 * i4 + 2] * rn * gn[2] * sigmoidf_(bflo(ow.y)), y3 = acc[vb][4 * i4 + 3] * rn * gn[3] * sigmoidf_(bfhi(ow.y));
;             u32x2 w; w.x = pk2(y0, y1); w.y = pk2(y2, y3); if (st) *(u32x2*)(orow + v0) = w; if (i4 == 3) asm volatile("" ::: "memory"); }
	v_lshlrev_b32_e32 v54, 16, v52
	v_and_b32_e32 v52, 0xffff0000, v52
	ds_bpermute_b32 v1, v125, v0
	v_mul_f32_e32 v52, 0xbfb8aa3b, v52
	v_add_f32_e32 v48, 1.0, v48
	v_exp_f32_e32 v52, v52
	v_rcp_f32_e32 v97, v48
	v_lshlrev_b32_e32 v48, 16, v49
	v_mul_f32_e32 v48, 0xbfb8aa3b, v48
	v_exp_f32_e32 v48, v48
	s_waitcnt lgkmcnt(0)
	v_add_f32_e32 v0, v0, v1
	v_mov_b32_e32 v2, 0x358637bd
	v_and_b32_e32 v87, 0xffff0000, v87
	v_add_f32_e32 v52, 1.0, v52
	v_fmamk_f32 v0, v0, 0x3c000000, v2
	v_mul_f32_e32 v84, 0xbfb8aa3b, v84
	v_mul_f32_e32 v85, 0xbfb8aa3b, v85
	v_mul_f32_e32 v86, 0xbfb8aa3b, v86
	v_mul_f32_e32 v87, 0xbfb8aa3b, v87
	v_rcp_f32_e32 v109, v52
	v_lshlrev_b32_e32 v52, 16, v53
	v_cmp_gt_f32_e32 vcc, s65, v0
	v_mul_f32_e32 v1, 0x4b800000, v0
	v_exp_f32_e32 v84, v84
	v_exp_f32_e32 v85, v85
	v_exp_f32_e32 v86, v86
	v_exp_f32_e32 v87, v87
	v_mul_f32_e32 v52, 0xbfb8aa3b, v52
	v_cndmask_b32_e32 v0, v0, v1, vcc
	v_add_f32_e32 v48, 1.0, v48
	v_exp_f32_e32 v52, v52
	v_rsq_f32_e32 v0, v0
	v_rcp_f32_e32 v98, v48
	v_and_b32_e32 v48, 0xffff0000, v49
	v_mul_f32_e32 v50, 0xbfb8aa3b, v50
	v_mul_f32_e32 v48, 0xbfb8aa3b, v48
	v_add_f32_e32 v84, 1.0, v84
	v_add_f32_e32 v85, 1.0, v85
	v_add_f32_e32 v86, 1.0, v86
	v_add_f32_e32 v87, 1.0, v87
	v_exp_f32_e32 v50, v50
	v_exp_f32_e32 v48, v48
	v_rcp_f32_e32 v84, v84
	v_rcp_f32_e32 v85, v85
	v_rcp_f32_e32 v86, v86
	v_rcp_f32_e32 v87, v87
	v_add_f32_e32 v52, 1.0, v52
	v_mul_f32_e32 v1, 0x45800000, v0
	v_rcp_f32_e32 v110, v52
	v_and_b32_e32 v52, 0xffff0000, v53
	v_cndmask_b32_e32 v4, v0, v1, vcc
	v_mul_f32_e32 v54, 0xbfb8aa3b, v54
	v_mul_f32_e32 v52, 0xbfb8aa3b, v52
	v_pk_mul_f32 v[0:1], v[90:91], v[4:5] op_sel_hi:[1,0]
	v_pk_mul_f32 v[2:3], v[88:89], v[4:5] op_sel_hi:[1,0]
	v_add_f32_e32 v50, 1.0, v50
	v_add_f32_e32 v48, 1.0, v48
	v_exp_f32_e32 v54, v54
	v_exp_f32_e32 v52, v52
	v_pk_mul_f32 v[0:1], v[64:65], v[0:1]
	v_pk_mul_f32 v[2:3], v[66:67], v[2:3]
	v_rcp_f32_e32 v96, v50
	v_rcp_f32_e32 v99, v48
	v_pk_mul_f32 v[0:1], v[84:85], v[0:1]
	v_pk_mul_f32 v[2:3], v[86:87], v[2:3]
	v_cvt_pk_bf16_f32 v0, v0, v1
	v_cvt_pk_bf16_f32 v1, v2, v3
	ds_read_b128 v[48:51], v81 offset:20544
	global_store_dwordx2 v[82:83], v[0:1], off
	v_pk_mul_f32 v[0:1], v[102:103], v[4:5] op_sel_hi:[1,0]
	v_pk_mul_f32 v[2:3], v[100:101], v[4:5] op_sel_hi:[1,0]
	v_add_f32_e32 v54, 1.0, v54
	v_add_f32_e32 v52, 1.0, v52
	v_pk_mul_f32 v[0:1], v[10:11], v[0:1]
	v_pk_mul_f32 v[2:3], v[12:13], v[2:3]
	v_rcp_f32_e32 v108, v54
	v_rcp_f32_e32 v111, v52
	v_pk_mul_f32 v[0:1], v[96:97], v[0:1]
	v_pk_mul_f32 v[2:3], v[98:99], v[2:3]
	v_cvt_pk_bf16_f32 v0, v0, v1
	v_cvt_pk_bf16_f32 v1, v2, v3
	ds_read_b128 v[52:55], v81 offset:20576
	global_store_dwordx2 v[70:71], v[0:1], off offset:16
	v_pk_mul_f32 v[0:1], v[56:57], v[4:5] op_sel_hi:[1,0]
	v_pk_mul_f32 v[2:3], v[58:59], v[4:5] op_sel_hi:[1,0]
	s_waitcnt lgkmcnt(1)
	v_pk_mul_f32 v[0:1], v[48:49], v[0:1]
	v_pk_mul_f32 v[2:3], v[50:51], v[2:3]
	v_pk_mul_f32 v[0:1], v[108:109], v[0:1]
	v_pk_mul_f32 v[2:3], v[110:111], v[2:3]
	v_cvt_pk_bf16_f32 v0, v0, v1
	v_cvt_pk_bf16_f32 v1, v2, v3
	global_store_dwordx2 v[70:71], v[0:1], off offset:32
	v_pk_mul_f32 v[0:1], v[130:131], v[4:5] op_sel_hi:[1,0]
	v_pk_mul_f32 v[2:3], v[126:127], v[4:5] op_sel_hi:[1,0]
	s_waitcnt lgkmcnt(0)
	v_pk_mul_f32 v[0:1], v[52:53], v[0:1]
	v_pk_mul_f32 v[2:3], v[54:55], v[2:3]
	v_pk_mul_f32 v[0:1], v[120:121], v[0:1]
	v_pk_mul_f32 v[2:3], v[122:123], v[2:3]
	v_cvt_pk_bf16_f32 v0, v0, v1
	v_cvt_pk_bf16_f32 v1, v2, v3
	global_store_dwordx2 v[70:71], v[0:1], off offset:48
	global_load_dwordx2 v[12:13], v[70:71], off offset:64
	ds_read_b128 v[0:3], v81 offset:20608
	ds_read_b128 v[8:11], v81 offset:20640
	s_waitcnt vmcnt(0)
	v_lshlrev_b32_e32 v5, 16, v12
	v_mul_f32_e32 v5, 0xbfb8aa3b, v5
	v_exp_f32_e32 v5, v5
	s_nop 0
	v_add_f32_e32 v5, 1.0, v5
	v_rcp_f32_e32 v28, v5
	v_pk_mul_f32 v[30:31], v[138:139], v[4:5] op_sel_hi:[1,0]
	v_and_b32_e32 v5, 0xffff0000, v12
	v_mul_f32_e32 v5, 0xbfb8aa3b, v5
	v_exp_f32_e32 v5, v5
	s_waitcnt lgkmcnt(1)
	v_pk_mul_f32 v[0:1], v[0:1], v[30:31]
	v_add_f32_e32 v5, 1.0, v5
	v_rcp_f32_e32 v29, v5
	v_lshlrev_b32_e32 v5, 16, v13
	v_mul_f32_e32 v5, 0xbfb8aa3b, v5
	v_exp_f32_e32 v5, v5
	v_pk_mul_f32 v[0:1], v[28:29], v[0:1]
	v_add_f32_e32 v5, 1.0, v5
	v_rcp_f32_e32 v12, v5
	v_pk_mul_f32 v[28:29], v[134:135], v[4:5] op_sel_hi:[1,0]
	v_and_b32_e32 v5, 0xffff0000, v13
	v_mul_f32_e32 v5, 0xbfb8aa3b, v5
	v_exp_f32_e32 v5, v5
	v_pk_mul_f32 v[2:3], v[2:3], v[28:29]
	v_cvt_pk_bf16_f32 v0, v0, v1
	v_add_f32_e32 v5, 1.0, v5
	v_rcp_f32_e32 v13, v5
	s_nop 0
	v_pk_mul_f32 v[2:3], v[12:13], v[2:3]
	s_nop 0
	v_cvt_pk_bf16_f32 v1, v2, v3
	global_store_dwordx2 v[70:71], v[0:1], off offset:64
	global_load_dwordx2 v[0:1], v[70:71], off offset:80
	v_pk_mul_f32 v[12:13], v[118:119], v[4:5] op_sel_hi:[1,0]
	s_waitcnt vmcnt(0)
	v_lshlrev_b32_e32 v2, 16, v0
	v_and_b32_e32 v0, 0xffff0000, v0
	v_mul_f32_e32 v0, 0xbfb8aa3b, v0
	v_exp_f32_e32 v0, v0
	v_mul_f32_e32 v2, 0xbfb8aa3b, v2
	v_exp_f32_e32 v2, v2
	s_waitcnt lgkmcnt(0)
	v_pk_mul_f32 v[8:9], v[8:9], v[12:13]
	v_add_f32_e32 v0, 1.0, v0
	v_rcp_f32_e32 v3, v0
	v_lshlrev_b32_e32 v0, 16, v1
	v_and_b32_e32 v1, 0xffff0000, v1
	v_mul_f32_e32 v0, 0xbfb8aa3b, v0
	v_mul_f32_e32 v1, 0xbfb8aa3b, v1
	v_exp_f32_e32 v0, v0
	v_exp_f32_e32 v1, v1
	v_add_f32_e32 v2, 1.0, v2
	v_rcp_f32_e32 v2, v2
	v_add_f32_e32 v0, 1.0, v0
	v_add_f32_e32 v1, 1.0, v1
	v_rcp_f32_e32 v0, v0
	v_rcp_f32_e32 v1, v1
	v_pk_mul_f32 v[2:3], v[2:3], v[8:9]
	v_pk_mul_f32 v[8:9], v[116:117], v[4:5] op_sel_hi:[1,0]
	v_cvt_pk_bf16_f32 v2, v2, v3
	v_pk_mul_f32 v[8:9], v[10:11], v[8:9]
	s_nop 0
	v_pk_mul_f32 v[0:1], v[0:1], v[8:9]
	global_load_dwordx2 v[8:9], v[70:71], off offset:96
	v_cvt_pk_bf16_f32 v3, v0, v1
	global_store_dwordx2 v[70:71], v[2:3], off offset:80
	ds_read_b128 v[0:3], v81 offset:20672
	s_waitcnt vmcnt(1)
; #define LAS __attribute__((address_space(3)))
; __device__ __forceinline__ unsigned pk2(float lo, float hi) { f32x2_t v = {lo, hi}; bf16x2_t b = __builtin_convertvector(v, bf16x2_t); return __builtin_bit_cast(unsigned, b); }
; __device__ __forceinline__ float bflo(unsigned w) { return __uint_as_float(w << 16); }
; __device__ __forceinline__ float bfhi(unsigned w) { return __uint_as_float(w & 0xffff0000u); }
; __device__ __forceinline__ float sigmoidf_(float x) { return __builtin_amdgcn_rcpf(1.f + fexp(-x)); }
; template <bool SAMPLE>
; __device__ __forceinline__ void mout_task(Ctx& C, int l, int unit, int h, int tb, const LAS float* cwl, const LAS float* gainl, LAS float* gsbuf, LAS s16x8* qfl, const bool st) {
;     ...
;         for (int i4 = 0; i4 < 4; ++i4) { const int v0 = 32 * vb + 8 * i4 + 4 * hi2;
;             const u32x2 ow = *(const u32x2*)(orow + v0); const f32x4 gn = *(const LAS f32x4*)(gainl + h * 128 + v0);
;             const float y0 = acc[vb][4 * i4] * rn * gn[0] * sigmoidf_(bflo(ow.x)), y1 = acc[vb][4 * i4 + 1] * rn * gn[1] * sigmoidf_(bfhi(ow.x));
;             const float y2 = acc[vb][4 * i4 + 2] * rn * gn[2] * sigmoidf_(bflo(ow.y)), y3 = acc[vb][4 * i4 + 3] * rn * gn[3] * sigmoidf_(bfhi(ow.y));
;             u32x2 w; w.x = pk2(y0, y1); w.y = pk2(y2, y3); if (st) *(u32x2*)(orow + v0) = w; if (i4 == 3) asm volatile("" ::: "memory"); }
	v_lshlrev_b32_e32 v5, 16, v8
	v_mul_f32_e32 v5, 0xbfb8aa3b, v5
	v_exp_f32_e32 v5, v5
	s_nop 0
	v_add_f32_e32 v5, 1.0, v5
	v_rcp_f32_e32 v10, v5
	v_pk_mul_f32 v[12:13], v[62:63], v[4:5] op_sel_hi:[1,0]
	v_and_b32_e32 v5, 0xffff0000, v8
	v_mul_f32_e32 v5, 0xbfb8aa3b, v5
	v_exp_f32_e32 v5, v5
	s_waitcnt lgkmcnt(0)
	v_pk_mul_f32 v[0:1], v[0:1], v[12:13]
	v_add_f32_e32 v5, 1.0, v5
	v_rcp_f32_e32 v11, v5
	v_lshlrev_b32_e32 v5, 16, v9
	v_mul_f32_e32 v5, 0xbfb8aa3b, v5
	v_exp_f32_e32 v5, v5
	v_pk_mul_f32 v[0:1], v[10:11], v[0:1]
	v_add_f32_e32 v5, 1.0, v5
	v_rcp_f32_e32 v8, v5
	v_pk_mul_f32 v[10:11], v[60:61], v[4:5] op_sel_hi:[1,0]
	v_and_b32_e32 v5, 0xffff0000, v9
	v_mul_f32_e32 v5, 0xbfb8aa3b, v5
	v_exp_f32_e32 v5, v5
	v_pk_mul_f32 v[2:3], v[2:3], v[10:11]
	v_cvt_pk_bf16_f32 v0, v0, v1
	v_add_f32_e32 v5, 1.0, v5
	v_rcp_f32_e32 v9, v5
	s_nop 0
	v_pk_mul_f32 v[2:3], v[8:9], v[2:3]
	global_load_dwordx2 v[8:9], v[70:71], off offset:112
	v_cvt_pk_bf16_f32 v1, v2, v3
	global_store_dwordx2 v[70:71], v[0:1], off offset:96
	ds_read_b128 v[0:3], v81 offset:20704
	s_waitcnt vmcnt(1)
	v_lshlrev_b32_e32 v5, 16, v8
	v_mul_f32_e32 v5, 0xbfb8aa3b, v5
	v_exp_f32_e32 v5, v5
	s_nop 0
	v_add_f32_e32 v5, 1.0, v5
	v_rcp_f32_e32 v10, v5
	v_pk_mul_f32 v[12:13], v[44:45], v[4:5] op_sel_hi:[1,0]
	v_and_b32_e32 v5, 0xffff0000, v8
	v_mul_f32_e32 v5, 0xbfb8aa3b, v5
	v_exp_f32_e32 v5, v5
	s_waitcnt lgkmcnt(0)
	v_pk_mul_f32 v[0:1], v[0:1], v[12:13]
	v_add_f32_e32 v5, 1.0, v5
	v_rcp_f32_e32 v11, v5
	v_lshlrev_b32_e32 v5, 16, v9
	v_mul_f32_e32 v5, 0xbfb8aa3b, v5
	v_exp_f32_e32 v5, v5
	v_pk_mul_f32 v[0:1], v[10:11], v[0:1]
	v_add_f32_e32 v5, 1.0, v5
	v_rcp_f32_e32 v8, v5
	v_pk_mul_f32 v[10:11], v[46:47], v[4:5] op_sel_hi:[1,0]
	v_and_b32_e32 v5, 0xffff0000, v9
	v_mul_f32_e32 v5, 0xbfb8aa3b, v5
	v_exp_f32_e32 v5, v5
	v_pk_mul_f32 v[2:3], v[2:3], v[10:11]
	v_cvt_pk_bf16_f32 v0, v0, v1
	v_add_f32_e32 v5, 1.0, v5
	v_rcp_f32_e32 v9, v5
	s_nop 0
	v_pk_mul_f32 v[2:3], v[8:9], v[2:3]
	s_nop 0
	v_cvt_pk_bf16_f32 v1, v2, v3
	global_store_dwordx2 v[70:71], v[0:1], off offset:112
	global_load_dwordx2 v[12:13], v[70:71], off offset:128
	ds_read_b128 v[0:3], v81 offset:20736
	ds_read_b128 v[8:11], v81 offset:20768
	s_waitcnt vmcnt(0)
	v_lshlrev_b32_e32 v5, 16, v12
	v_mul_f32_e32 v5, 0xbfb8aa3b, v5
	v_exp_f32_e32 v5, v5
	s_nop 0
	v_add_f32_e32 v5, 1.0, v5
	v_rcp_f32_e32 v28, v5
	v_pk_mul_f32 v[30:31], v[42:43], v[4:5] op_sel_hi:[1,0]
	v_and_b32_e32 v5, 0xffff0000, v12
	v_mul_f32_e32 v5, 0xbfb8aa3b, v5
	v_exp_f32_e32 v5, v5
	s_waitcnt lgkmcnt(1)
	v_pk_mul_f32 v[0:1], v[0:1], v[30:31]
	v_add_f32_e32 v5, 1.0, v5
	v_rcp_f32_e32 v29, v5
	v_lshlrev_b32_e32 v5, 16, v13
	v_mul_f32_e32 v5, 0xbfb8aa3b, v5
	v_exp_f32_e32 v5, v5
	v_pk_mul_f32 v[0:1], v[28:29], v[0:1]
	v_add_f32_e32 v5, 1.0, v5
	v_rcp_f32_e32 v12, v5
	v_pk_mul_f32 v[28:29], v[40:41], v[4:5] op_sel_hi:[1,0]
	v_and_b32_e32 v5, 0xffff0000, v13
	v_mul_f32_e32 v5, 0xbfb8aa3b, v5
	v_exp_f32_e32 v5, v5
	v_pk_mul_f32 v[2:3], v[2:3], v[28:29]
	v_cvt_pk_bf16_f32 v0, v0, v1
	v_add_f32_e32 v5, 1.0, v5
	v_rcp_f32_e32 v13, v5
	s_nop 0
	v_pk_mul_f32 v[2:3], v[12:13], v[2:3]
	s_nop 0
	v_cvt_pk_bf16_f32 v1, v2, v3
	global_store_dwordx2 v[70:71], v[0:1], off offset:128
	global_load_dwordx2 v[0:1], v[70:71], off offset:144
	v_pk_mul_f32 v[12:13], v[38:39], v[4:5] op_sel_hi:[1,0]
	s_waitcnt vmcnt(0)
	v_lshlrev_b32_e32 v2, 16, v0
	v_and_b32_e32 v0, 0xffff0000, v0
	v_mul_f32_e32 v0, 0xbfb8aa3b, v0
	v_exp_f32_e32 v0, v0
	v_mul_f32_e32 v2, 0xbfb8aa3b, v2
	v_exp_f32_e32 v2, v2
	s_waitcnt lgkmcnt(0)
	v_pk_mul_f32 v[8:9], v[8:9], v[12:13]
	v_add_f32_e32 v0, 1.0, v0
	v_rcp_f32_e32 v3, v0
	v_lshlrev_b32_e32 v0, 16, v1
	v_and_b32_e32 v1, 0xffff0000, v1
	v_mul_f32_e32 v0, 0xbfb8aa3b, v0
	v_mul_f32_e32 v1, 0xbfb8aa3b, v1
	v_exp_f32_e32 v0, v0
	v_exp_f32_e32 v1, v1
	v_add_f32_e32 v2, 1.0, v2
	v_rcp_f32_e32 v2, v2
	v_add_f32_e32 v0, 1.0, v0
	v_add_f32_e32 v1, 1.0, v1
	v_rcp_f32_e32 v0, v0
	v_rcp_f32_e32 v1, v1
	v_pk_mul_f32 v[2:3], v[2:3], v[8:9]
	v_pk_mul_f32 v[8:9], v[36:37], v[4:5] op_sel_hi:[1,0]
	v_cvt_pk_bf16_f32 v2, v2, v3
	v_pk_mul_f32 v[8:9], v[10:11], v[8:9]
	s_nop 0
	v_pk_mul_f32 v[0:1], v[0:1], v[8:9]
	global_load_dwordx2 v[8:9], v[70:71], off offset:160
	v_cvt_pk_bf16_f32 v3, v0, v1
	global_store_dwordx2 v[70:71], v[2:3], off offset:144
	ds_read_b128 v[0:3], v81 offset:20800
	s_waitcnt vmcnt(1)
	v_lshlrev_b32_e32 v5, 16, v8
	v_mul_f32_e32 v5, 0xbfb8aa3b, v5
	v_exp_f32_e32 v5, v5
	s_nop 0
	v_add_f32_e32 v5, 1.0, v5
	v_rcp_f32_e32 v10, v5
	v_pk_mul_f32 v[12:13], v[34:35], v[4:5] op_sel_hi:[1,0]
	v_and_b32_e32 v5, 0xffff0000, v8
	v_mul_f32_e32 v5, 0xbfb8aa3b, v5
	v_exp_f32_e32 v5, v5
	s_waitcnt lgkmcnt(0)
	v_pk_mul_f32 v[0:1], v[0:1], v[12:13]
	v_add_f32_e32 v5, 1.0, v5
	v_rcp_f32_e32 v11, v5
	v_lshlrev_b32_e32 v5, 16, v9
	v_mul_f32_e32 v5, 0xbfb8aa3b, v5
	v_exp_f32_e32 v5, v5
	v_pk_mul_f32 v[0:1], v[10:11], v[0:1]
	v_add_f32_e32 v5, 1.0, v5
	v_rcp_f32_e32 v8, v5
	v_pk_mul_f32 v[10:11], v[32:33], v[4:5] op_sel_hi:[1,0]
	v_and_b32_e32 v5, 0xffff0000, v9
	v_mul_f32_e32 v5, 0xbfb8aa3b, v5
	v_exp_f32_e32 v5, v5
	v_pk_mul_f32 v[2:3], v[2:3], v[10:11]
	v_cvt_pk_bf16_f32 v0, v0, v1
	v_add_f32_e32 v5, 1.0, v5
	v_rcp_f32_e32 v9, v5
	s_nop 0
	v_pk_mul_f32 v[2:3], v[8:9], v[2:3]
	global_load_dwordx2 v[8:9], v[70:71], off offset:176
	v_cvt_pk_bf16_f32 v1, v2, v3
	global_store_dwordx2 v[70:71], v[0:1], off offset:160
	ds_read_b128 v[0:3], v81 offset:20832
	s_waitcnt vmcnt(1)
; #define LAS __attribute__((address_space(3)))
; __device__ __forceinline__ unsigned pk2(float lo, float hi) { f32x2_t v = {lo, hi}; bf16x2_t b = __builtin_convertvector(v, bf16x2_t); return __builtin_bit_cast(unsigned, b); }
; __device__ __forceinline__ float bflo(unsigned w) { return __uint_as_float(w << 16); }
; __device__ __forceinline__ float bfhi(unsigned w) { return __uint_as_float(w & 0xffff0000u); }
; __device__ __forceinline__ float sigmoidf_(float x) { return __builtin_amdgcn_rcpf(1.f + fexp(-x)); }
; #define LDS_WAIT() asm volatile("s_waitcnt lgkmcnt(0)" ::: "memory")
; template <bool SAMPLE>
; __device__ __forceinline__ void mout_task(Ctx& C, int l, int unit, int h, int tb, const LAS float* cwl, const LAS float* gainl, LAS float* gsbuf, LAS s16x8* qfl, const bool st) {
;     ...
;         for (int i4 = 0; i4 < 4; ++i4) { const int v0 = 32 * vb + 8 * i4 + 4 * hi2;
;             const u32x2 ow = *(const u32x2*)(orow + v0); const f32x4 gn = *(const LAS f32x4*)(gainl + h * 128 + v0);
;             const float y0 = acc[vb][4 * i4] * rn * gn[0] * sigmoidf_(bflo(ow.x)), y1 = acc[vb][4 * i4 + 1] * rn * gn[1] * sigmoidf_(bfhi(ow.x));
;             const float y2 = acc[vb][4 * i4 + 2] * rn * gn[2] * sigmoidf_(bflo(ow.y)), y3 = acc[vb][4 * i4 + 3] * rn * gn[3] * sigmoidf_(bfhi(ow.y));
;             u32x2 w; w.x = pk2(y0, y1); w.y = pk2(y2, y3); if (st) *(u32x2*)(orow + v0) = w; if (i4 == 3) asm volatile("" ::: "memory"); }
;     LDS_WAIT();
	v_lshlrev_b32_e32 v5, 16, v8
	v_mul_f32_e32 v5, 0xbfb8aa3b, v5
	v_exp_f32_e32 v5, v5
	s_nop 0
	v_add_f32_e32 v5, 1.0, v5
	v_rcp_f32_e32 v10, v5
	v_pk_mul_f32 v[12:13], v[26:27], v[4:5] op_sel_hi:[1,0]
	v_and_b32_e32 v5, 0xffff0000, v8
	v_mul_f32_e32 v5, 0xbfb8aa3b, v5
	v_exp_f32_e32 v5, v5
	s_waitcnt lgkmcnt(0)
	v_pk_mul_f32 v[0:1], v[0:1], v[12:13]
	v_add_f32_e32 v5, 1.0, v5
	v_rcp_f32_e32 v11, v5
	v_lshlrev_b32_e32 v5, 16, v9
	v_mul_f32_e32 v5, 0xbfb8aa3b, v5
	v_exp_f32_e32 v5, v5
	v_pk_mul_f32 v[0:1], v[10:11], v[0:1]
	v_add_f32_e32 v5, 1.0, v5
	v_rcp_f32_e32 v8, v5
	v_pk_mul_f32 v[10:11], v[24:25], v[4:5] op_sel_hi:[1,0]
	v_and_b32_e32 v5, 0xffff0000, v9
	v_mul_f32_e32 v5, 0xbfb8aa3b, v5
	v_exp_f32_e32 v5, v5
	v_pk_mul_f32 v[2:3], v[2:3], v[10:11]
	v_cvt_pk_bf16_f32 v0, v0, v1
	v_add_f32_e32 v5, 1.0, v5
	v_rcp_f32_e32 v9, v5
	s_nop 0
	v_pk_mul_f32 v[2:3], v[8:9], v[2:3]
	s_nop 0
	v_cvt_pk_bf16_f32 v1, v2, v3
	global_store_dwordx2 v[70:71], v[0:1], off offset:176
	global_load_dwordx2 v[12:13], v[70:71], off offset:192
	ds_read_b128 v[0:3], v81 offset:20864
	ds_read_b128 v[8:11], v81 offset:20896
	s_waitcnt vmcnt(0)
	v_lshlrev_b32_e32 v5, 16, v12
	v_mul_f32_e32 v5, 0xbfb8aa3b, v5
	v_exp_f32_e32 v5, v5
	s_nop 0
	v_add_f32_e32 v5, 1.0, v5
	v_rcp_f32_e32 v24, v5
	v_pk_mul_f32 v[22:23], v[22:23], v[4:5] op_sel_hi:[1,0]
	v_and_b32_e32 v5, 0xffff0000, v12
	v_mul_f32_e32 v5, 0xbfb8aa3b, v5
	v_exp_f32_e32 v5, v5
	s_waitcnt lgkmcnt(1)
	v_pk_mul_f32 v[0:1], v[0:1], v[22:23]
	v_add_f32_e32 v5, 1.0, v5
	v_rcp_f32_e32 v25, v5
	v_lshlrev_b32_e32 v5, 16, v13
	v_mul_f32_e32 v5, 0xbfb8aa3b, v5
	v_exp_f32_e32 v5, v5
	v_pk_mul_f32 v[0:1], v[24:25], v[0:1]
	v_add_f32_e32 v5, 1.0, v5
	v_rcp_f32_e32 v12, v5
	v_pk_mul_f32 v[20:21], v[20:21], v[4:5] op_sel_hi:[1,0]
	v_and_b32_e32 v5, 0xffff0000, v13
	v_mul_f32_e32 v5, 0xbfb8aa3b, v5
	v_exp_f32_e32 v5, v5
	v_pk_mul_f32 v[2:3], v[2:3], v[20:21]
	v_cvt_pk_bf16_f32 v0, v0, v1
	v_add_f32_e32 v5, 1.0, v5
	v_rcp_f32_e32 v13, v5
	s_nop 0
	v_pk_mul_f32 v[2:3], v[12:13], v[2:3]
	s_nop 0
	v_cvt_pk_bf16_f32 v1, v2, v3
	global_store_dwordx2 v[70:71], v[0:1], off offset:192
	global_load_dwordx2 v[0:1], v[70:71], off offset:208
	v_pk_mul_f32 v[12:13], v[18:19], v[4:5] op_sel_hi:[1,0]
	s_waitcnt vmcnt(0)
	v_lshlrev_b32_e32 v2, 16, v0
	v_and_b32_e32 v0, 0xffff0000, v0
	v_mul_f32_e32 v0, 0xbfb8aa3b, v0
	v_exp_f32_e32 v0, v0
	v_mul_f32_e32 v2, 0xbfb8aa3b, v2
	v_exp_f32_e32 v2, v2
	s_waitcnt lgkmcnt(0)
	v_pk_mul_f32 v[8:9], v[8:9], v[12:13]
	v_add_f32_e32 v0, 1.0, v0
	v_rcp_f32_e32 v3, v0
	v_lshlrev_b32_e32 v0, 16, v1
	v_and_b32_e32 v1, 0xffff0000, v1
	v_mul_f32_e32 v0, 0xbfb8aa3b, v0
	v_mul_f32_e32 v1, 0xbfb8aa3b, v1
	v_exp_f32_e32 v0, v0
	v_exp_f32_e32 v1, v1
	v_add_f32_e32 v2, 1.0, v2
	v_rcp_f32_e32 v2, v2
	v_add_f32_e32 v0, 1.0, v0
	v_add_f32_e32 v1, 1.0, v1
	v_rcp_f32_e32 v0, v0
	v_rcp_f32_e32 v1, v1
	v_pk_mul_f32 v[2:3], v[2:3], v[8:9]
	v_pk_mul_f32 v[8:9], v[16:17], v[4:5] op_sel_hi:[1,0]
	v_cvt_pk_bf16_f32 v2, v2, v3
	v_pk_mul_f32 v[8:9], v[10:11], v[8:9]
	s_nop 0
	v_pk_mul_f32 v[0:1], v[0:1], v[8:9]
	global_load_dwordx2 v[8:9], v[70:71], off offset:224
	v_cvt_pk_bf16_f32 v3, v0, v1
	global_store_dwordx2 v[70:71], v[2:3], off offset:208
	ds_read_b128 v[0:3], v81 offset:20928
	s_waitcnt vmcnt(1)
	v_lshlrev_b32_e32 v5, 16, v8
	v_mul_f32_e32 v5, 0xbfb8aa3b, v5
	v_exp_f32_e32 v5, v5
	s_nop 0
	v_add_f32_e32 v5, 1.0, v5
	v_rcp_f32_e32 v10, v5
	v_pk_mul_f32 v[6:7], v[6:7], v[4:5] op_sel_hi:[1,0]
	v_and_b32_e32 v5, 0xffff0000, v8
	v_mul_f32_e32 v5, 0xbfb8aa3b, v5
	v_exp_f32_e32 v5, v5
	s_waitcnt lgkmcnt(0)
	v_pk_mul_f32 v[0:1], v[0:1], v[6:7]
	v_add_f32_e32 v5, 1.0, v5
	v_rcp_f32_e32 v11, v5
	v_lshlrev_b32_e32 v5, 16, v9
	v_mul_f32_e32 v5, 0xbfb8aa3b, v5
	v_exp_f32_e32 v5, v5
	v_pk_mul_f32 v[0:1], v[10:11], v[0:1]
	v_add_f32_e32 v5, 1.0, v5
	v_rcp_f32_e32 v6, v5
	v_and_b32_e32 v5, 0xffff0000, v9
	v_mul_f32_e32 v5, 0xbfb8aa3b, v5
	v_exp_f32_e32 v5, v5
	v_cvt_pk_bf16_f32 v0, v0, v1
	v_add_f32_e32 v5, 1.0, v5
	v_rcp_f32_e32 v7, v5
	v_pk_mul_f32 v[8:9], v[72:73], v[4:5] op_sel_hi:[1,0]
	s_nop 0
	v_pk_mul_f32 v[2:3], v[2:3], v[8:9]
	s_nop 0
	v_pk_mul_f32 v[2:3], v[6:7], v[2:3]
	global_load_dwordx2 v[6:7], v[70:71], off offset:240
	v_cvt_pk_bf16_f32 v1, v2, v3
	global_store_dwordx2 v[70:71], v[0:1], off offset:224
	ds_read_b128 v[0:3], v81 offset:20960
	s_waitcnt vmcnt(1)
	v_lshlrev_b32_e32 v5, 16, v6
	v_mul_f32_e32 v5, 0xbfb8aa3b, v5
	v_exp_f32_e32 v5, v5
	s_nop 0
	v_add_f32_e32 v5, 1.0, v5
	v_rcp_f32_e32 v8, v5
	v_and_b32_e32 v5, 0xffff0000, v6
	v_mul_f32_e32 v5, 0xbfb8aa3b, v5
	v_exp_f32_e32 v5, v5
	s_nop 0
	v_add_f32_e32 v5, 1.0, v5
	v_rcp_f32_e32 v9, v5
	v_pk_mul_f32 v[10:11], v[68:69], v[4:5] op_sel_hi:[1,0]
	v_lshlrev_b32_e32 v5, 16, v7
	v_mul_f32_e32 v5, 0xbfb8aa3b, v5
	v_exp_f32_e32 v5, v5
	s_waitcnt lgkmcnt(0)
	v_pk_mul_f32 v[0:1], v[0:1], v[10:11]
	v_add_f32_e32 v5, 1.0, v5
	v_rcp_f32_e32 v6, v5
	v_and_b32_e32 v5, 0xffff0000, v7
	v_mul_f32_e32 v5, 0xbfb8aa3b, v5
	v_exp_f32_e32 v5, v5
	v_pk_mul_f32 v[0:1], v[8:9], v[0:1]
	v_add_f32_e32 v5, 1.0, v5
	v_rcp_f32_e32 v7, v5
	v_pk_mul_f32 v[4:5], v[14:15], v[4:5] op_sel_hi:[1,0]
	v_cvt_pk_bf16_f32 v0, v0, v1
	v_pk_mul_f32 v[2:3], v[2:3], v[4:5]
	s_nop 0
	v_pk_mul_f32 v[2:3], v[6:7], v[2:3]
	s_nop 0
	v_cvt_pk_bf16_f32 v1, v2, v3
	global_store_dwordx2 v[70:71], v[0:1], off offset:240
	s_waitcnt lgkmcnt(0)
	s_branch .LBB0_903
